# hand-scheduled RWKV scan inner loop (32 steps unrolled, LDS reads in one block, no nops, S*w+v*k precomputed off the reduction chain) + barrier: leader XGEN release before its own L1 invalidate
# speedup vs baseline: 1.0214x; 1.0214x over previous
.LBB0_125:
	s_or_b64 exec, exec, s[4:5]
	s_mov_b64 s[4:5], exec
	v_mbcnt_lo_u32_b32 v0, s4, 0
	v_mbcnt_hi_u32_b32 v0, s5, v0
	v_cmp_eq_u32_e32 vcc, 0, v0
	s_waitcnt vmcnt(0)
	s_and_saveexec_b64 s[6:7], vcc
	s_cbranch_execz .LBB0_127
	s_bcnt1_i32_b64 s4, s[4:5]
	v_mov_b32_e32 v0, 0x2000
	v_mov_b32_e32 v1, s4
	global_atomic_add v0, v1, s[2:3] offset:1024
.LBB0_127:
	s_or_b64 exec, exec, s[6:7]
	buffer_inv sc1
	s_waitcnt vmcnt(0)

.LBB0_486:
	s_and_b64 vcc, exec, s[52:53]
	s_cbranch_vccz .LBB0_477
	s_mul_hi_u32 s44, s61, 0xaaaaaaab
	s_lshr_b32 s44, s44, 1
	s_bitcmp1_b32 s61, 0
	s_cselect_b32 s62, 0xb000, 0
	s_add_i32 s53, s61, 2
	s_and_b32 s54, s53, 0xff
	s_mulk_i32 s54, 0xab
	s_bfe_u32 s54, s54, 0x70009
	s_mul_i32 s54, s54, 3
	s_sub_i32 s53, s53, s54
	s_and_b32 s53, s53, 0xff
	s_lshl_b32 s63, s53, 12
	v_add_u32_e32 v239, s62, v157
	v_lshl_add_u32 v240, v124, 2, s62
	ds_read_b128 v[44:47], v239 offset:24576
	ds_read_b128 v[48:51], v239 offset:24592
	ds_read_b128 v[52:55], v239 offset:32768
	ds_read_b128 v[56:59], v239 offset:32784
	ds_read_b32 v84, v240 offset:40960
	ds_read_b128 v[60:63], v239 offset:16384
	ds_read_b128 v[64:67], v239 offset:16400
	ds_read_b128 v[68:71], v239 offset:8192
	ds_read_b128 v[72:75], v239 offset:8208
	ds_read_b128 v[76:79], v239 offset:0
	ds_read_b128 v[80:83], v239 offset:16
	s_mulk_i32 s44, 0xd000
	v_add_u32_e32 v241, s44, v167
	v_add_u32_e32 v242, s63, v127
	ds_read_b128 v[182:185], v239 offset:24832
	ds_read_b128 v[186:189], v239 offset:24848
	ds_read_b128 v[190:193], v239 offset:33024
	ds_read_b128 v[194:197], v239 offset:33040
	ds_read_b32 v222, v240 offset:41088
	ds_read_b128 v[198:201], v239 offset:16640
	ds_read_b128 v[202:205], v239 offset:16656
	ds_read_b128 v[206:209], v239 offset:8448
	ds_read_b128 v[210:213], v239 offset:8464
	ds_read_b128 v[214:217], v239 offset:256
	ds_read_b128 v[218:221], v239 offset:272
	s_waitcnt lgkmcnt(11)
	v_pk_mul_f32 v[224:225], v[148:149], v[44:45]
	v_pk_mul_f32 v[228:229], v[60:61], v[84:85] op_sel_hi:[1,0]
	v_pk_fma_f32 v[224:225], v[150:151], v[46:47], v[224:225]
	v_pk_mul_f32 v[230:231], v[62:63], v[84:85] op_sel_hi:[1,0]
	v_pk_fma_f32 v[224:225], v[152:153], v[48:49], v[224:225]
	v_pk_mul_f32 v[232:233], v[64:65], v[84:85] op_sel_hi:[1,0]
	v_pk_fma_f32 v[224:225], v[154:155], v[50:51], v[224:225]
	v_pk_mul_f32 v[234:235], v[66:67], v[84:85] op_sel_hi:[1,0]
	v_pk_fma_f32 v[228:229], v[148:149], v[68:69], v[228:229]
	v_add_f32_e32 v226, v224, v225
	v_add_f32_dpp v238, v169, v169 quad_perm:[1,0,3,2] row_mask:0xf bank_mask:0xf bound_ctrl:1
	v_pk_fma_f32 v[230:231], v[150:151], v[70:71], v[230:231]
	v_add_f32_dpp v226, v226, v226 quad_perm:[1,0,3,2] row_mask:0xf bank_mask:0xf bound_ctrl:1
	v_add_f32_dpp v238, v238, v238 quad_perm:[2,3,0,1] row_mask:0xf bank_mask:0xf bound_ctrl:1
	v_pk_fma_f32 v[232:233], v[152:153], v[72:73], v[232:233]
	v_add_f32_dpp v226, v226, v226 quad_perm:[2,3,0,1] row_mask:0xf bank_mask:0xf bound_ctrl:1
	v_add_f32_dpp v238, v238, v238 row_half_mirror row_mask:0xf bank_mask:0xf bound_ctrl:1
	v_pk_fma_f32 v[234:235], v[154:155], v[74:75], v[234:235]
	v_add_f32_dpp v226, v226, v226 row_half_mirror row_mask:0xf bank_mask:0xf bound_ctrl:1
	v_pk_fma_f32 v[148:149], v[52:53], v[226:227], v[228:229] op_sel_hi:[1,0,1]
	v_pk_fma_f32 v[150:151], v[54:55], v[226:227], v[230:231] op_sel_hi:[1,0,1]
	v_pk_mul_f32 v[236:237], v[148:149], v[76:77]
	v_pk_fma_f32 v[152:153], v[56:57], v[226:227], v[232:233] op_sel_hi:[1,0,1]
	v_pk_fma_f32 v[236:237], v[150:151], v[78:79], v[236:237]
	v_pk_fma_f32 v[154:155], v[58:59], v[226:227], v[234:235] op_sel_hi:[1,0,1]
	v_pk_fma_f32 v[236:237], v[152:153], v[80:81], v[236:237]
	v_cndmask_b32_e64 v168, v168, v238, s[4:5]
	v_pk_fma_f32 v[236:237], v[154:155], v[82:83], v[236:237]
	ds_write_b32 v242, v168 offset:3072
	ds_read_b128 v[44:47], v239 offset:25088
	ds_read_b128 v[48:51], v239 offset:25104
	ds_read_b128 v[52:55], v239 offset:33280
	ds_read_b128 v[56:59], v239 offset:33296
	ds_read_b32 v84, v240 offset:41216
	ds_read_b128 v[60:63], v239 offset:16896
	ds_read_b128 v[64:67], v239 offset:16912
	ds_read_b128 v[68:71], v239 offset:8704
	ds_read_b128 v[72:75], v239 offset:8720
	ds_read_b128 v[76:79], v239 offset:512
	ds_read_b128 v[80:83], v239 offset:528
	s_waitcnt lgkmcnt(11)
	v_add_f32_e32 v169, v236, v237
	v_pk_mul_f32 v[224:225], v[148:149], v[182:183]
	v_pk_mul_f32 v[228:229], v[198:199], v[222:223] op_sel_hi:[1,0]
	v_pk_fma_f32 v[224:225], v[150:151], v[184:185], v[224:225]
	v_pk_mul_f32 v[230:231], v[200:201], v[222:223] op_sel_hi:[1,0]
	v_pk_fma_f32 v[224:225], v[152:153], v[186:187], v[224:225]
	v_pk_mul_f32 v[232:233], v[202:203], v[222:223] op_sel_hi:[1,0]
	v_pk_fma_f32 v[224:225], v[154:155], v[188:189], v[224:225]
	v_pk_mul_f32 v[234:235], v[204:205], v[222:223] op_sel_hi:[1,0]
	v_pk_fma_f32 v[228:229], v[148:149], v[206:207], v[228:229]
	v_add_f32_e32 v226, v224, v225
	v_add_f32_dpp v238, v169, v169 quad_perm:[1,0,3,2] row_mask:0xf bank_mask:0xf bound_ctrl:1
	v_pk_fma_f32 v[230:231], v[150:151], v[208:209], v[230:231]
	v_add_f32_dpp v226, v226, v226 quad_perm:[1,0,3,2] row_mask:0xf bank_mask:0xf bound_ctrl:1
	v_add_f32_dpp v238, v238, v238 quad_perm:[2,3,0,1] row_mask:0xf bank_mask:0xf bound_ctrl:1
	v_pk_fma_f32 v[232:233], v[152:153], v[210:211], v[232:233]
	v_add_f32_dpp v226, v226, v226 quad_perm:[2,3,0,1] row_mask:0xf bank_mask:0xf bound_ctrl:1
	v_add_f32_dpp v238, v238, v238 row_half_mirror row_mask:0xf bank_mask:0xf bound_ctrl:1
	v_pk_fma_f32 v[234:235], v[154:155], v[212:213], v[234:235]
	v_add_f32_dpp v226, v226, v226 row_half_mirror row_mask:0xf bank_mask:0xf bound_ctrl:1
	v_pk_fma_f32 v[148:149], v[190:191], v[226:227], v[228:229] op_sel_hi:[1,0,1]
	v_pk_fma_f32 v[150:151], v[192:193], v[226:227], v[230:231] op_sel_hi:[1,0,1]
	v_pk_mul_f32 v[236:237], v[148:149], v[214:215]
	v_pk_fma_f32 v[152:153], v[194:195], v[226:227], v[232:233] op_sel_hi:[1,0,1]
	v_pk_fma_f32 v[236:237], v[150:151], v[216:217], v[236:237]
	v_pk_fma_f32 v[154:155], v[196:197], v[226:227], v[234:235] op_sel_hi:[1,0,1]
	v_pk_fma_f32 v[236:237], v[152:153], v[218:219], v[236:237]
	v_cndmask_b32_e64 v168, v168, v238, s[6:7]
	v_pk_fma_f32 v[236:237], v[154:155], v[220:221], v[236:237]
	ds_read_b128 v[182:185], v239 offset:25344
	ds_read_b128 v[186:189], v239 offset:25360
	ds_read_b128 v[190:193], v239 offset:33536
	ds_read_b128 v[194:197], v239 offset:33552
	ds_read_b32 v222, v240 offset:41344
	ds_read_b128 v[198:201], v239 offset:17152
	ds_read_b128 v[202:205], v239 offset:17168
	ds_read_b128 v[206:209], v239 offset:8960
	ds_read_b128 v[210:213], v239 offset:8976
	ds_read_b128 v[214:217], v239 offset:768
	ds_read_b128 v[218:221], v239 offset:784
	s_waitcnt lgkmcnt(11)
	v_add_f32_e32 v169, v236, v237
	v_pk_mul_f32 v[224:225], v[148:149], v[44:45]
	v_pk_mul_f32 v[228:229], v[60:61], v[84:85] op_sel_hi:[1,0]
	v_pk_fma_f32 v[224:225], v[150:151], v[46:47], v[224:225]
	v_pk_mul_f32 v[230:231], v[62:63], v[84:85] op_sel_hi:[1,0]
	v_pk_fma_f32 v[224:225], v[152:153], v[48:49], v[224:225]
	v_pk_mul_f32 v[232:233], v[64:65], v[84:85] op_sel_hi:[1,0]
	v_pk_fma_f32 v[224:225], v[154:155], v[50:51], v[224:225]
	v_pk_mul_f32 v[234:235], v[66:67], v[84:85] op_sel_hi:[1,0]
	v_pk_fma_f32 v[228:229], v[148:149], v[68:69], v[228:229]
	v_add_f32_e32 v226, v224, v225
	v_add_f32_dpp v238, v169, v169 quad_perm:[1,0,3,2] row_mask:0xf bank_mask:0xf bound_ctrl:1
	v_pk_fma_f32 v[230:231], v[150:151], v[70:71], v[230:231]
	v_add_f32_dpp v226, v226, v226 quad_perm:[1,0,3,2] row_mask:0xf bank_mask:0xf bound_ctrl:1
	v_add_f32_dpp v238, v238, v238 quad_perm:[2,3,0,1] row_mask:0xf bank_mask:0xf bound_ctrl:1
	v_pk_fma_f32 v[232:233], v[152:153], v[72:73], v[232:233]
	v_add_f32_dpp v226, v226, v226 quad_perm:[2,3,0,1] row_mask:0xf bank_mask:0xf bound_ctrl:1
	v_add_f32_dpp v238, v238, v238 row_half_mirror row_mask:0xf bank_mask:0xf bound_ctrl:1
	v_pk_fma_f32 v[234:235], v[154:155], v[74:75], v[234:235]
	v_add_f32_dpp v226, v226, v226 row_half_mirror row_mask:0xf bank_mask:0xf bound_ctrl:1
	v_pk_fma_f32 v[148:149], v[52:53], v[226:227], v[228:229] op_sel_hi:[1,0,1]
	v_pk_fma_f32 v[150:151], v[54:55], v[226:227], v[230:231] op_sel_hi:[1,0,1]
	v_pk_mul_f32 v[236:237], v[148:149], v[76:77]
	v_pk_fma_f32 v[152:153], v[56:57], v[226:227], v[232:233] op_sel_hi:[1,0,1]
	v_pk_fma_f32 v[236:237], v[150:151], v[78:79], v[236:237]
	v_pk_fma_f32 v[154:155], v[58:59], v[226:227], v[234:235] op_sel_hi:[1,0,1]
	v_pk_fma_f32 v[236:237], v[152:153], v[80:81], v[236:237]
	v_cndmask_b32_e64 v168, v168, v238, s[8:9]
	v_pk_fma_f32 v[236:237], v[154:155], v[82:83], v[236:237]
	ds_read_b128 v[44:47], v239 offset:25600
	ds_read_b128 v[48:51], v239 offset:25616
	ds_read_b128 v[52:55], v239 offset:33792
	ds_read_b128 v[56:59], v239 offset:33808
	ds_read_b32 v84, v240 offset:41472
	ds_read_b128 v[60:63], v239 offset:17408
	ds_read_b128 v[64:67], v239 offset:17424
	ds_read_b128 v[68:71], v239 offset:9216
	ds_read_b128 v[72:75], v239 offset:9232
	ds_read_b128 v[76:79], v239 offset:1024
	ds_read_b128 v[80:83], v239 offset:1040
	s_waitcnt lgkmcnt(11)
	v_add_f32_e32 v169, v236, v237
	v_pk_mul_f32 v[224:225], v[148:149], v[182:183]
	v_pk_mul_f32 v[228:229], v[198:199], v[222:223] op_sel_hi:[1,0]
	v_pk_fma_f32 v[224:225], v[150:151], v[184:185], v[224:225]
	v_pk_mul_f32 v[230:231], v[200:201], v[222:223] op_sel_hi:[1,0]
	v_pk_fma_f32 v[224:225], v[152:153], v[186:187], v[224:225]
	v_pk_mul_f32 v[232:233], v[202:203], v[222:223] op_sel_hi:[1,0]
	v_pk_fma_f32 v[224:225], v[154:155], v[188:189], v[224:225]
	v_pk_mul_f32 v[234:235], v[204:205], v[222:223] op_sel_hi:[1,0]
	v_pk_fma_f32 v[228:229], v[148:149], v[206:207], v[228:229]
	v_add_f32_e32 v226, v224, v225
	v_add_f32_dpp v238, v169, v169 quad_perm:[1,0,3,2] row_mask:0xf bank_mask:0xf bound_ctrl:1
	v_pk_fma_f32 v[230:231], v[150:151], v[208:209], v[230:231]
	v_add_f32_dpp v226, v226, v226 quad_perm:[1,0,3,2] row_mask:0xf bank_mask:0xf bound_ctrl:1
	v_add_f32_dpp v238, v238, v238 quad_perm:[2,3,0,1] row_mask:0xf bank_mask:0xf bound_ctrl:1
	v_pk_fma_f32 v[232:233], v[152:153], v[210:211], v[232:233]
	v_add_f32_dpp v226, v226, v226 quad_perm:[2,3,0,1] row_mask:0xf bank_mask:0xf bound_ctrl:1
	v_add_f32_dpp v238, v238, v238 row_half_mirror row_mask:0xf bank_mask:0xf bound_ctrl:1
	v_pk_fma_f32 v[234:235], v[154:155], v[212:213], v[234:235]
	v_add_f32_dpp v226, v226, v226 row_half_mirror row_mask:0xf bank_mask:0xf bound_ctrl:1
	v_pk_fma_f32 v[148:149], v[190:191], v[226:227], v[228:229] op_sel_hi:[1,0,1]
	v_pk_fma_f32 v[150:151], v[192:193], v[226:227], v[230:231] op_sel_hi:[1,0,1]
	v_pk_mul_f32 v[236:237], v[148:149], v[214:215]
	v_pk_fma_f32 v[152:153], v[194:195], v[226:227], v[232:233] op_sel_hi:[1,0,1]
	v_pk_fma_f32 v[236:237], v[150:151], v[216:217], v[236:237]
	v_pk_fma_f32 v[154:155], v[196:197], v[226:227], v[234:235] op_sel_hi:[1,0,1]
	v_pk_fma_f32 v[236:237], v[152:153], v[218:219], v[236:237]
	v_cndmask_b32_e64 v168, v168, v238, s[10:11]
	v_pk_fma_f32 v[236:237], v[154:155], v[220:221], v[236:237]
	ds_read_b128 v[182:185], v239 offset:25856
	ds_read_b128 v[186:189], v239 offset:25872
	ds_read_b128 v[190:193], v239 offset:34048
	ds_read_b128 v[194:197], v239 offset:34064
	ds_read_b32 v222, v240 offset:41600
	ds_read_b128 v[198:201], v239 offset:17664
	ds_read_b128 v[202:205], v239 offset:17680
	ds_read_b128 v[206:209], v239 offset:9472
	ds_read_b128 v[210:213], v239 offset:9488
	ds_read_b128 v[214:217], v239 offset:1280
	ds_read_b128 v[218:221], v239 offset:1296
	s_waitcnt lgkmcnt(11)
	v_add_f32_e32 v169, v236, v237
	v_pk_mul_f32 v[224:225], v[148:149], v[44:45]
	v_pk_mul_f32 v[228:229], v[60:61], v[84:85] op_sel_hi:[1,0]
	v_pk_fma_f32 v[224:225], v[150:151], v[46:47], v[224:225]
	v_pk_mul_f32 v[230:231], v[62:63], v[84:85] op_sel_hi:[1,0]
	v_pk_fma_f32 v[224:225], v[152:153], v[48:49], v[224:225]
	v_pk_mul_f32 v[232:233], v[64:65], v[84:85] op_sel_hi:[1,0]
	v_pk_fma_f32 v[224:225], v[154:155], v[50:51], v[224:225]
	v_pk_mul_f32 v[234:235], v[66:67], v[84:85] op_sel_hi:[1,0]
	v_pk_fma_f32 v[228:229], v[148:149], v[68:69], v[228:229]
	v_add_f32_e32 v226, v224, v225
	v_add_f32_dpp v238, v169, v169 quad_perm:[1,0,3,2] row_mask:0xf bank_mask:0xf bound_ctrl:1
	v_pk_fma_f32 v[230:231], v[150:151], v[70:71], v[230:231]
	v_add_f32_dpp v226, v226, v226 quad_perm:[1,0,3,2] row_mask:0xf bank_mask:0xf bound_ctrl:1
	v_add_f32_dpp v238, v238, v238 quad_perm:[2,3,0,1] row_mask:0xf bank_mask:0xf bound_ctrl:1
	v_pk_fma_f32 v[232:233], v[152:153], v[72:73], v[232:233]
	v_add_f32_dpp v226, v226, v226 quad_perm:[2,3,0,1] row_mask:0xf bank_mask:0xf bound_ctrl:1
	v_add_f32_dpp v238, v238, v238 row_half_mirror row_mask:0xf bank_mask:0xf bound_ctrl:1
	v_pk_fma_f32 v[234:235], v[154:155], v[74:75], v[234:235]
	v_add_f32_dpp v226, v226, v226 row_half_mirror row_mask:0xf bank_mask:0xf bound_ctrl:1
	v_pk_fma_f32 v[148:149], v[52:53], v[226:227], v[228:229] op_sel_hi:[1,0,1]
	v_pk_fma_f32 v[150:151], v[54:55], v[226:227], v[230:231] op_sel_hi:[1,0,1]
	v_pk_mul_f32 v[236:237], v[148:149], v[76:77]
	v_pk_fma_f32 v[152:153], v[56:57], v[226:227], v[232:233] op_sel_hi:[1,0,1]
	v_pk_fma_f32 v[236:237], v[150:151], v[78:79], v[236:237]
	v_pk_fma_f32 v[154:155], v[58:59], v[226:227], v[234:235] op_sel_hi:[1,0,1]
	v_pk_fma_f32 v[236:237], v[152:153], v[80:81], v[236:237]
	v_cndmask_b32_e64 v168, v168, v238, s[12:13]
	v_pk_fma_f32 v[236:237], v[154:155], v[82:83], v[236:237]
	ds_read_b128 v[44:47], v239 offset:26112
	ds_read_b128 v[48:51], v239 offset:26128
	ds_read_b128 v[52:55], v239 offset:34304
	ds_read_b128 v[56:59], v239 offset:34320
	ds_read_b32 v84, v240 offset:41728
	ds_read_b128 v[60:63], v239 offset:17920
	ds_read_b128 v[64:67], v239 offset:17936
	ds_read_b128 v[68:71], v239 offset:9728
	ds_read_b128 v[72:75], v239 offset:9744
	ds_read_b128 v[76:79], v239 offset:1536
	ds_read_b128 v[80:83], v239 offset:1552
	s_waitcnt lgkmcnt(11)
	v_add_f32_e32 v169, v236, v237
	v_pk_mul_f32 v[224:225], v[148:149], v[182:183]
	v_pk_mul_f32 v[228:229], v[198:199], v[222:223] op_sel_hi:[1,0]
	v_pk_fma_f32 v[224:225], v[150:151], v[184:185], v[224:225]
	v_pk_mul_f32 v[230:231], v[200:201], v[222:223] op_sel_hi:[1,0]
	v_pk_fma_f32 v[224:225], v[152:153], v[186:187], v[224:225]
	v_pk_mul_f32 v[232:233], v[202:203], v[222:223] op_sel_hi:[1,0]
	v_pk_fma_f32 v[224:225], v[154:155], v[188:189], v[224:225]
	v_pk_mul_f32 v[234:235], v[204:205], v[222:223] op_sel_hi:[1,0]
	v_pk_fma_f32 v[228:229], v[148:149], v[206:207], v[228:229]
	v_add_f32_e32 v226, v224, v225
	v_add_f32_dpp v238, v169, v169 quad_perm:[1,0,3,2] row_mask:0xf bank_mask:0xf bound_ctrl:1
	v_pk_fma_f32 v[230:231], v[150:151], v[208:209], v[230:231]
	v_add_f32_dpp v226, v226, v226 quad_perm:[1,0,3,2] row_mask:0xf bank_mask:0xf bound_ctrl:1
	v_add_f32_dpp v238, v238, v238 quad_perm:[2,3,0,1] row_mask:0xf bank_mask:0xf bound_ctrl:1
	v_pk_fma_f32 v[232:233], v[152:153], v[210:211], v[232:233]
	v_add_f32_dpp v226, v226, v226 quad_perm:[2,3,0,1] row_mask:0xf bank_mask:0xf bound_ctrl:1
	v_add_f32_dpp v238, v238, v238 row_half_mirror row_mask:0xf bank_mask:0xf bound_ctrl:1
	v_pk_fma_f32 v[234:235], v[154:155], v[212:213], v[234:235]
	v_add_f32_dpp v226, v226, v226 row_half_mirror row_mask:0xf bank_mask:0xf bound_ctrl:1
	v_pk_fma_f32 v[148:149], v[190:191], v[226:227], v[228:229] op_sel_hi:[1,0,1]
	v_pk_fma_f32 v[150:151], v[192:193], v[226:227], v[230:231] op_sel_hi:[1,0,1]
	v_pk_mul_f32 v[236:237], v[148:149], v[214:215]
	v_pk_fma_f32 v[152:153], v[194:195], v[226:227], v[232:233] op_sel_hi:[1,0,1]
	v_pk_fma_f32 v[236:237], v[150:151], v[216:217], v[236:237]
	v_pk_fma_f32 v[154:155], v[196:197], v[226:227], v[234:235] op_sel_hi:[1,0,1]
	v_pk_fma_f32 v[236:237], v[152:153], v[218:219], v[236:237]
	v_cndmask_b32_e64 v168, v168, v238, s[14:15]
	v_pk_fma_f32 v[236:237], v[154:155], v[220:221], v[236:237]
	ds_read_b128 v[182:185], v239 offset:26368
	ds_read_b128 v[186:189], v239 offset:26384
	ds_read_b128 v[190:193], v239 offset:34560
	ds_read_b128 v[194:197], v239 offset:34576
	ds_read_b32 v222, v240 offset:41856
	ds_read_b128 v[198:201], v239 offset:18176
	ds_read_b128 v[202:205], v239 offset:18192
	ds_read_b128 v[206:209], v239 offset:9984
	ds_read_b128 v[210:213], v239 offset:10000
	ds_read_b128 v[214:217], v239 offset:1792
	ds_read_b128 v[218:221], v239 offset:1808
	s_waitcnt lgkmcnt(11)
	v_add_f32_e32 v169, v236, v237
	v_pk_mul_f32 v[224:225], v[148:149], v[44:45]
	v_pk_mul_f32 v[228:229], v[60:61], v[84:85] op_sel_hi:[1,0]
	v_pk_fma_f32 v[224:225], v[150:151], v[46:47], v[224:225]
	v_pk_mul_f32 v[230:231], v[62:63], v[84:85] op_sel_hi:[1,0]
	v_pk_fma_f32 v[224:225], v[152:153], v[48:49], v[224:225]
	v_pk_mul_f32 v[232:233], v[64:65], v[84:85] op_sel_hi:[1,0]
	v_pk_fma_f32 v[224:225], v[154:155], v[50:51], v[224:225]
	v_pk_mul_f32 v[234:235], v[66:67], v[84:85] op_sel_hi:[1,0]
	v_pk_fma_f32 v[228:229], v[148:149], v[68:69], v[228:229]
	v_add_f32_e32 v226, v224, v225
	v_add_f32_dpp v238, v169, v169 quad_perm:[1,0,3,2] row_mask:0xf bank_mask:0xf bound_ctrl:1
	v_pk_fma_f32 v[230:231], v[150:151], v[70:71], v[230:231]
	v_add_f32_dpp v226, v226, v226 quad_perm:[1,0,3,2] row_mask:0xf bank_mask:0xf bound_ctrl:1
	v_add_f32_dpp v238, v238, v238 quad_perm:[2,3,0,1] row_mask:0xf bank_mask:0xf bound_ctrl:1
	v_pk_fma_f32 v[232:233], v[152:153], v[72:73], v[232:233]
	v_add_f32_dpp v226, v226, v226 quad_perm:[2,3,0,1] row_mask:0xf bank_mask:0xf bound_ctrl:1
	v_add_f32_dpp v238, v238, v238 row_half_mirror row_mask:0xf bank_mask:0xf bound_ctrl:1
	v_pk_fma_f32 v[234:235], v[154:155], v[74:75], v[234:235]
	v_add_f32_dpp v226, v226, v226 row_half_mirror row_mask:0xf bank_mask:0xf bound_ctrl:1
	v_pk_fma_f32 v[148:149], v[52:53], v[226:227], v[228:229] op_sel_hi:[1,0,1]
	v_pk_fma_f32 v[150:151], v[54:55], v[226:227], v[230:231] op_sel_hi:[1,0,1]
	v_pk_mul_f32 v[236:237], v[148:149], v[76:77]
	v_pk_fma_f32 v[152:153], v[56:57], v[226:227], v[232:233] op_sel_hi:[1,0,1]
	v_pk_fma_f32 v[236:237], v[150:151], v[78:79], v[236:237]
	v_pk_fma_f32 v[154:155], v[58:59], v[226:227], v[234:235] op_sel_hi:[1,0,1]
	v_pk_fma_f32 v[236:237], v[152:153], v[80:81], v[236:237]
	v_cndmask_b32_e64 v168, v168, v238, s[16:17]
	v_pk_fma_f32 v[236:237], v[154:155], v[82:83], v[236:237]
	ds_read_b128 v[44:47], v239 offset:26624
	ds_read_b128 v[48:51], v239 offset:26640
	ds_read_b128 v[52:55], v239 offset:34816
	ds_read_b128 v[56:59], v239 offset:34832
	ds_read_b32 v84, v240 offset:41984
	ds_read_b128 v[60:63], v239 offset:18432
	ds_read_b128 v[64:67], v239 offset:18448
	ds_read_b128 v[68:71], v239 offset:10240
	ds_read_b128 v[72:75], v239 offset:10256
	ds_read_b128 v[76:79], v239 offset:2048
	ds_read_b128 v[80:83], v239 offset:2064
	s_waitcnt lgkmcnt(11)
	v_add_f32_e32 v169, v236, v237
	v_pk_mul_f32 v[224:225], v[148:149], v[182:183]
	v_pk_mul_f32 v[228:229], v[198:199], v[222:223] op_sel_hi:[1,0]
	v_pk_fma_f32 v[224:225], v[150:151], v[184:185], v[224:225]
	v_pk_mul_f32 v[230:231], v[200:201], v[222:223] op_sel_hi:[1,0]
	v_pk_fma_f32 v[224:225], v[152:153], v[186:187], v[224:225]
	v_pk_mul_f32 v[232:233], v[202:203], v[222:223] op_sel_hi:[1,0]
	v_pk_fma_f32 v[224:225], v[154:155], v[188:189], v[224:225]
	v_pk_mul_f32 v[234:235], v[204:205], v[222:223] op_sel_hi:[1,0]
	v_pk_fma_f32 v[228:229], v[148:149], v[206:207], v[228:229]
	v_add_f32_e32 v226, v224, v225
	v_add_f32_dpp v238, v169, v169 quad_perm:[1,0,3,2] row_mask:0xf bank_mask:0xf bound_ctrl:1
	v_pk_fma_f32 v[230:231], v[150:151], v[208:209], v[230:231]
	v_add_f32_dpp v226, v226, v226 quad_perm:[1,0,3,2] row_mask:0xf bank_mask:0xf bound_ctrl:1
	v_add_f32_dpp v238, v238, v238 quad_perm:[2,3,0,1] row_mask:0xf bank_mask:0xf bound_ctrl:1
	v_pk_fma_f32 v[232:233], v[152:153], v[210:211], v[232:233]
	v_add_f32_dpp v226, v226, v226 quad_perm:[2,3,0,1] row_mask:0xf bank_mask:0xf bound_ctrl:1
	v_add_f32_dpp v238, v238, v238 row_half_mirror row_mask:0xf bank_mask:0xf bound_ctrl:1
	v_pk_fma_f32 v[234:235], v[154:155], v[212:213], v[234:235]
	v_add_f32_dpp v226, v226, v226 row_half_mirror row_mask:0xf bank_mask:0xf bound_ctrl:1
	v_pk_fma_f32 v[148:149], v[190:191], v[226:227], v[228:229] op_sel_hi:[1,0,1]
	v_pk_fma_f32 v[150:151], v[192:193], v[226:227], v[230:231] op_sel_hi:[1,0,1]
	v_pk_mul_f32 v[236:237], v[148:149], v[214:215]
	v_pk_fma_f32 v[152:153], v[194:195], v[226:227], v[232:233] op_sel_hi:[1,0,1]
	v_pk_fma_f32 v[236:237], v[150:151], v[216:217], v[236:237]
	v_pk_fma_f32 v[154:155], v[196:197], v[226:227], v[234:235] op_sel_hi:[1,0,1]
	v_pk_fma_f32 v[236:237], v[152:153], v[218:219], v[236:237]
	v_cndmask_b32_e64 v168, v168, v238, s[18:19]
	v_pk_fma_f32 v[236:237], v[154:155], v[220:221], v[236:237]
	ds_read_b128 v[182:185], v239 offset:26880
	ds_read_b128 v[186:189], v239 offset:26896
	ds_read_b128 v[190:193], v239 offset:35072
	ds_read_b128 v[194:197], v239 offset:35088
	ds_read_b32 v222, v240 offset:42112
	ds_read_b128 v[198:201], v239 offset:18688
	ds_read_b128 v[202:205], v239 offset:18704
	ds_read_b128 v[206:209], v239 offset:10496
	ds_read_b128 v[210:213], v239 offset:10512
	ds_read_b128 v[214:217], v239 offset:2304
	ds_read_b128 v[218:221], v239 offset:2320
	s_waitcnt lgkmcnt(11)
	v_add_f32_e32 v169, v236, v237
	v_pk_mul_f32 v[224:225], v[148:149], v[44:45]
	v_pk_mul_f32 v[228:229], v[60:61], v[84:85] op_sel_hi:[1,0]
	v_pk_fma_f32 v[224:225], v[150:151], v[46:47], v[224:225]
	v_pk_mul_f32 v[230:231], v[62:63], v[84:85] op_sel_hi:[1,0]
	v_pk_fma_f32 v[224:225], v[152:153], v[48:49], v[224:225]
	v_pk_mul_f32 v[232:233], v[64:65], v[84:85] op_sel_hi:[1,0]
	v_pk_fma_f32 v[224:225], v[154:155], v[50:51], v[224:225]
	v_pk_mul_f32 v[234:235], v[66:67], v[84:85] op_sel_hi:[1,0]
	v_pk_fma_f32 v[228:229], v[148:149], v[68:69], v[228:229]
	v_add_f32_e32 v226, v224, v225
	v_add_f32_dpp v238, v169, v169 quad_perm:[1,0,3,2] row_mask:0xf bank_mask:0xf bound_ctrl:1
	v_pk_fma_f32 v[230:231], v[150:151], v[70:71], v[230:231]
	v_add_f32_dpp v226, v226, v226 quad_perm:[1,0,3,2] row_mask:0xf bank_mask:0xf bound_ctrl:1
	v_add_f32_dpp v238, v238, v238 quad_perm:[2,3,0,1] row_mask:0xf bank_mask:0xf bound_ctrl:1
	v_pk_fma_f32 v[232:233], v[152:153], v[72:73], v[232:233]
	v_add_f32_dpp v226, v226, v226 quad_perm:[2,3,0,1] row_mask:0xf bank_mask:0xf bound_ctrl:1
	v_add_f32_dpp v238, v238, v238 row_half_mirror row_mask:0xf bank_mask:0xf bound_ctrl:1
	v_pk_fma_f32 v[234:235], v[154:155], v[74:75], v[234:235]
	v_add_f32_dpp v226, v226, v226 row_half_mirror row_mask:0xf bank_mask:0xf bound_ctrl:1
	v_pk_fma_f32 v[148:149], v[52:53], v[226:227], v[228:229] op_sel_hi:[1,0,1]
	v_pk_fma_f32 v[150:151], v[54:55], v[226:227], v[230:231] op_sel_hi:[1,0,1]
	v_pk_mul_f32 v[236:237], v[148:149], v[76:77]
	v_pk_fma_f32 v[152:153], v[56:57], v[226:227], v[232:233] op_sel_hi:[1,0,1]
	v_pk_fma_f32 v[236:237], v[150:151], v[78:79], v[236:237]
	v_pk_fma_f32 v[154:155], v[58:59], v[226:227], v[234:235] op_sel_hi:[1,0,1]
	v_pk_fma_f32 v[236:237], v[152:153], v[80:81], v[236:237]
	v_cndmask_b32_e64 v168, v168, v238, s[4:5]
	v_pk_fma_f32 v[236:237], v[154:155], v[82:83], v[236:237]
	ds_write_b32 v241, v168 offset:1024
	ds_read_b128 v[44:47], v239 offset:27136
	ds_read_b128 v[48:51], v239 offset:27152
	ds_read_b128 v[52:55], v239 offset:35328
	ds_read_b128 v[56:59], v239 offset:35344
	ds_read_b32 v84, v240 offset:42240
	ds_read_b128 v[60:63], v239 offset:18944
	ds_read_b128 v[64:67], v239 offset:18960
	ds_read_b128 v[68:71], v239 offset:10752
	ds_read_b128 v[72:75], v239 offset:10768
	ds_read_b128 v[76:79], v239 offset:2560
	ds_read_b128 v[80:83], v239 offset:2576
	s_waitcnt lgkmcnt(11)
	v_add_f32_e32 v169, v236, v237
	v_pk_mul_f32 v[224:225], v[148:149], v[182:183]
	v_pk_mul_f32 v[228:229], v[198:199], v[222:223] op_sel_hi:[1,0]
	v_pk_fma_f32 v[224:225], v[150:151], v[184:185], v[224:225]
	v_pk_mul_f32 v[230:231], v[200:201], v[222:223] op_sel_hi:[1,0]
	v_pk_fma_f32 v[224:225], v[152:153], v[186:187], v[224:225]
	v_pk_mul_f32 v[232:233], v[202:203], v[222:223] op_sel_hi:[1,0]
	v_pk_fma_f32 v[224:225], v[154:155], v[188:189], v[224:225]
	v_pk_mul_f32 v[234:235], v[204:205], v[222:223] op_sel_hi:[1,0]
	v_pk_fma_f32 v[228:229], v[148:149], v[206:207], v[228:229]
	v_add_f32_e32 v226, v224, v225
	v_add_f32_dpp v238, v169, v169 quad_perm:[1,0,3,2] row_mask:0xf bank_mask:0xf bound_ctrl:1
	v_pk_fma_f32 v[230:231], v[150:151], v[208:209], v[230:231]
	v_add_f32_dpp v226, v226, v226 quad_perm:[1,0,3,2] row_mask:0xf bank_mask:0xf bound_ctrl:1
	v_add_f32_dpp v238, v238, v238 quad_perm:[2,3,0,1] row_mask:0xf bank_mask:0xf bound_ctrl:1
	v_pk_fma_f32 v[232:233], v[152:153], v[210:211], v[232:233]
	v_add_f32_dpp v226, v226, v226 quad_perm:[2,3,0,1] row_mask:0xf bank_mask:0xf bound_ctrl:1
	v_add_f32_dpp v238, v238, v238 row_half_mirror row_mask:0xf bank_mask:0xf bound_ctrl:1
	v_pk_fma_f32 v[234:235], v[154:155], v[212:213], v[234:235]
	v_add_f32_dpp v226, v226, v226 row_half_mirror row_mask:0xf bank_mask:0xf bound_ctrl:1
	v_pk_fma_f32 v[148:149], v[190:191], v[226:227], v[228:229] op_sel_hi:[1,0,1]
	v_pk_fma_f32 v[150:151], v[192:193], v[226:227], v[230:231] op_sel_hi:[1,0,1]
	v_pk_mul_f32 v[236:237], v[148:149], v[214:215]
	v_pk_fma_f32 v[152:153], v[194:195], v[226:227], v[232:233] op_sel_hi:[1,0,1]
	v_pk_fma_f32 v[236:237], v[150:151], v[216:217], v[236:237]
	v_pk_fma_f32 v[154:155], v[196:197], v[226:227], v[234:235] op_sel_hi:[1,0,1]
	v_pk_fma_f32 v[236:237], v[152:153], v[218:219], v[236:237]
	v_cndmask_b32_e64 v168, v168, v238, s[6:7]
	v_pk_fma_f32 v[236:237], v[154:155], v[220:221], v[236:237]
	ds_read_b128 v[182:185], v239 offset:27392
	ds_read_b128 v[186:189], v239 offset:27408
	ds_read_b128 v[190:193], v239 offset:35584
	ds_read_b128 v[194:197], v239 offset:35600
	ds_read_b32 v222, v240 offset:42368
	ds_read_b128 v[198:201], v239 offset:19200
	ds_read_b128 v[202:205], v239 offset:19216
	ds_read_b128 v[206:209], v239 offset:11008
	ds_read_b128 v[210:213], v239 offset:11024
	ds_read_b128 v[214:217], v239 offset:2816
	ds_read_b128 v[218:221], v239 offset:2832
	s_waitcnt lgkmcnt(11)
	v_add_f32_e32 v169, v236, v237
	v_pk_mul_f32 v[224:225], v[148:149], v[44:45]
	v_pk_mul_f32 v[228:229], v[60:61], v[84:85] op_sel_hi:[1,0]
	v_pk_fma_f32 v[224:225], v[150:151], v[46:47], v[224:225]
	v_pk_mul_f32 v[230:231], v[62:63], v[84:85] op_sel_hi:[1,0]
	v_pk_fma_f32 v[224:225], v[152:153], v[48:49], v[224:225]
	v_pk_mul_f32 v[232:233], v[64:65], v[84:85] op_sel_hi:[1,0]
	v_pk_fma_f32 v[224:225], v[154:155], v[50:51], v[224:225]
	v_pk_mul_f32 v[234:235], v[66:67], v[84:85] op_sel_hi:[1,0]
	v_pk_fma_f32 v[228:229], v[148:149], v[68:69], v[228:229]
	v_add_f32_e32 v226, v224, v225
	v_add_f32_dpp v238, v169, v169 quad_perm:[1,0,3,2] row_mask:0xf bank_mask:0xf bound_ctrl:1
	v_pk_fma_f32 v[230:231], v[150:151], v[70:71], v[230:231]
	v_add_f32_dpp v226, v226, v226 quad_perm:[1,0,3,2] row_mask:0xf bank_mask:0xf bound_ctrl:1
	v_add_f32_dpp v238, v238, v238 quad_perm:[2,3,0,1] row_mask:0xf bank_mask:0xf bound_ctrl:1
	v_pk_fma_f32 v[232:233], v[152:153], v[72:73], v[232:233]
	v_add_f32_dpp v226, v226, v226 quad_perm:[2,3,0,1] row_mask:0xf bank_mask:0xf bound_ctrl:1
	v_add_f32_dpp v238, v238, v238 row_half_mirror row_mask:0xf bank_mask:0xf bound_ctrl:1
	v_pk_fma_f32 v[234:235], v[154:155], v[74:75], v[234:235]
	v_add_f32_dpp v226, v226, v226 row_half_mirror row_mask:0xf bank_mask:0xf bound_ctrl:1
	v_pk_fma_f32 v[148:149], v[52:53], v[226:227], v[228:229] op_sel_hi:[1,0,1]
	v_pk_fma_f32 v[150:151], v[54:55], v[226:227], v[230:231] op_sel_hi:[1,0,1]
	v_pk_mul_f32 v[236:237], v[148:149], v[76:77]
	v_pk_fma_f32 v[152:153], v[56:57], v[226:227], v[232:233] op_sel_hi:[1,0,1]
	v_pk_fma_f32 v[236:237], v[150:151], v[78:79], v[236:237]
	v_pk_fma_f32 v[154:155], v[58:59], v[226:227], v[234:235] op_sel_hi:[1,0,1]
	v_pk_fma_f32 v[236:237], v[152:153], v[80:81], v[236:237]
	v_cndmask_b32_e64 v168, v168, v238, s[8:9]
	v_pk_fma_f32 v[236:237], v[154:155], v[82:83], v[236:237]
	ds_read_b128 v[44:47], v239 offset:27648
	ds_read_b128 v[48:51], v239 offset:27664
	ds_read_b128 v[52:55], v239 offset:35840
	ds_read_b128 v[56:59], v239 offset:35856
	ds_read_b32 v84, v240 offset:42496
	ds_read_b128 v[60:63], v239 offset:19456
	ds_read_b128 v[64:67], v239 offset:19472
	ds_read_b128 v[68:71], v239 offset:11264
	ds_read_b128 v[72:75], v239 offset:11280
	ds_read_b128 v[76:79], v239 offset:3072
	ds_read_b128 v[80:83], v239 offset:3088
	s_waitcnt lgkmcnt(11)
	v_add_f32_e32 v169, v236, v237
	v_pk_mul_f32 v[224:225], v[148:149], v[182:183]
	v_pk_mul_f32 v[228:229], v[198:199], v[222:223] op_sel_hi:[1,0]
	v_pk_fma_f32 v[224:225], v[150:151], v[184:185], v[224:225]
	v_pk_mul_f32 v[230:231], v[200:201], v[222:223] op_sel_hi:[1,0]
	v_pk_fma_f32 v[224:225], v[152:153], v[186:187], v[224:225]
	v_pk_mul_f32 v[232:233], v[202:203], v[222:223] op_sel_hi:[1,0]
	v_pk_fma_f32 v[224:225], v[154:155], v[188:189], v[224:225]
	v_pk_mul_f32 v[234:235], v[204:205], v[222:223] op_sel_hi:[1,0]
	v_pk_fma_f32 v[228:229], v[148:149], v[206:207], v[228:229]
	v_add_f32_e32 v226, v224, v225
	v_add_f32_dpp v238, v169, v169 quad_perm:[1,0,3,2] row_mask:0xf bank_mask:0xf bound_ctrl:1
	v_pk_fma_f32 v[230:231], v[150:151], v[208:209], v[230:231]
	v_add_f32_dpp v226, v226, v226 quad_perm:[1,0,3,2] row_mask:0xf bank_mask:0xf bound_ctrl:1
	v_add_f32_dpp v238, v238, v238 quad_perm:[2,3,0,1] row_mask:0xf bank_mask:0xf bound_ctrl:1
	v_pk_fma_f32 v[232:233], v[152:153], v[210:211], v[232:233]
	v_add_f32_dpp v226, v226, v226 quad_perm:[2,3,0,1] row_mask:0xf bank_mask:0xf bound_ctrl:1
	v_add_f32_dpp v238, v238, v238 row_half_mirror row_mask:0xf bank_mask:0xf bound_ctrl:1
	v_pk_fma_f32 v[234:235], v[154:155], v[212:213], v[234:235]
	v_add_f32_dpp v226, v226, v226 row_half_mirror row_mask:0xf bank_mask:0xf bound_ctrl:1
	v_pk_fma_f32 v[148:149], v[190:191], v[226:227], v[228:229] op_sel_hi:[1,0,1]
	v_pk_fma_f32 v[150:151], v[192:193], v[226:227], v[230:231] op_sel_hi:[1,0,1]
	v_pk_mul_f32 v[236:237], v[148:149], v[214:215]
	v_pk_fma_f32 v[152:153], v[194:195], v[226:227], v[232:233] op_sel_hi:[1,0,1]
	v_pk_fma_f32 v[236:237], v[150:151], v[216:217], v[236:237]
	v_pk_fma_f32 v[154:155], v[196:197], v[226:227], v[234:235] op_sel_hi:[1,0,1]
	v_pk_fma_f32 v[236:237], v[152:153], v[218:219], v[236:237]
	v_cndmask_b32_e64 v168, v168, v238, s[10:11]
	v_pk_fma_f32 v[236:237], v[154:155], v[220:221], v[236:237]
	ds_read_b128 v[182:185], v239 offset:27904
	ds_read_b128 v[186:189], v239 offset:27920
	ds_read_b128 v[190:193], v239 offset:36096
	ds_read_b128 v[194:197], v239 offset:36112
	ds_read_b32 v222, v240 offset:42624
	ds_read_b128 v[198:201], v239 offset:19712
	ds_read_b128 v[202:205], v239 offset:19728
	ds_read_b128 v[206:209], v239 offset:11520
	ds_read_b128 v[210:213], v239 offset:11536
	ds_read_b128 v[214:217], v239 offset:3328
	ds_read_b128 v[218:221], v239 offset:3344
	s_waitcnt lgkmcnt(11)
	v_add_f32_e32 v169, v236, v237
	v_pk_mul_f32 v[224:225], v[148:149], v[44:45]
	v_pk_mul_f32 v[228:229], v[60:61], v[84:85] op_sel_hi:[1,0]
	v_pk_fma_f32 v[224:225], v[150:151], v[46:47], v[224:225]
	v_pk_mul_f32 v[230:231], v[62:63], v[84:85] op_sel_hi:[1,0]
	v_pk_fma_f32 v[224:225], v[152:153], v[48:49], v[224:225]
	v_pk_mul_f32 v[232:233], v[64:65], v[84:85] op_sel_hi:[1,0]
	v_pk_fma_f32 v[224:225], v[154:155], v[50:51], v[224:225]
	v_pk_mul_f32 v[234:235], v[66:67], v[84:85] op_sel_hi:[1,0]
	v_pk_fma_f32 v[228:229], v[148:149], v[68:69], v[228:229]
	v_add_f32_e32 v226, v224, v225
	v_add_f32_dpp v238, v169, v169 quad_perm:[1,0,3,2] row_mask:0xf bank_mask:0xf bound_ctrl:1
	v_pk_fma_f32 v[230:231], v[150:151], v[70:71], v[230:231]
	v_add_f32_dpp v226, v226, v226 quad_perm:[1,0,3,2] row_mask:0xf bank_mask:0xf bound_ctrl:1
	v_add_f32_dpp v238, v238, v238 quad_perm:[2,3,0,1] row_mask:0xf bank_mask:0xf bound_ctrl:1
	v_pk_fma_f32 v[232:233], v[152:153], v[72:73], v[232:233]
	v_add_f32_dpp v226, v226, v226 quad_perm:[2,3,0,1] row_mask:0xf bank_mask:0xf bound_ctrl:1
	v_add_f32_dpp v238, v238, v238 row_half_mirror row_mask:0xf bank_mask:0xf bound_ctrl:1
	v_pk_fma_f32 v[234:235], v[154:155], v[74:75], v[234:235]
	v_add_f32_dpp v226, v226, v226 row_half_mirror row_mask:0xf bank_mask:0xf bound_ctrl:1
	v_pk_fma_f32 v[148:149], v[52:53], v[226:227], v[228:229] op_sel_hi:[1,0,1]
	v_pk_fma_f32 v[150:151], v[54:55], v[226:227], v[230:231] op_sel_hi:[1,0,1]
	v_pk_mul_f32 v[236:237], v[148:149], v[76:77]
	v_pk_fma_f32 v[152:153], v[56:57], v[226:227], v[232:233] op_sel_hi:[1,0,1]
	v_pk_fma_f32 v[236:237], v[150:151], v[78:79], v[236:237]
	v_pk_fma_f32 v[154:155], v[58:59], v[226:227], v[234:235] op_sel_hi:[1,0,1]
	v_pk_fma_f32 v[236:237], v[152:153], v[80:81], v[236:237]
	v_cndmask_b32_e64 v168, v168, v238, s[12:13]
	v_pk_fma_f32 v[236:237], v[154:155], v[82:83], v[236:237]
	ds_read_b128 v[44:47], v239 offset:28160
	ds_read_b128 v[48:51], v239 offset:28176
	ds_read_b128 v[52:55], v239 offset:36352
	ds_read_b128 v[56:59], v239 offset:36368
	ds_read_b32 v84, v240 offset:42752
	ds_read_b128 v[60:63], v239 offset:19968
	ds_read_b128 v[64:67], v239 offset:19984
	ds_read_b128 v[68:71], v239 offset:11776
	ds_read_b128 v[72:75], v239 offset:11792
	ds_read_b128 v[76:79], v239 offset:3584
	ds_read_b128 v[80:83], v239 offset:3600
	s_waitcnt lgkmcnt(11)
	v_add_f32_e32 v169, v236, v237
	v_pk_mul_f32 v[224:225], v[148:149], v[182:183]
	v_pk_mul_f32 v[228:229], v[198:199], v[222:223] op_sel_hi:[1,0]
	v_pk_fma_f32 v[224:225], v[150:151], v[184:185], v[224:225]
	v_pk_mul_f32 v[230:231], v[200:201], v[222:223] op_sel_hi:[1,0]
	v_pk_fma_f32 v[224:225], v[152:153], v[186:187], v[224:225]
	v_pk_mul_f32 v[232:233], v[202:203], v[222:223] op_sel_hi:[1,0]
	v_pk_fma_f32 v[224:225], v[154:155], v[188:189], v[224:225]
	v_pk_mul_f32 v[234:235], v[204:205], v[222:223] op_sel_hi:[1,0]
	v_pk_fma_f32 v[228:229], v[148:149], v[206:207], v[228:229]
	v_add_f32_e32 v226, v224, v225
	v_add_f32_dpp v238, v169, v169 quad_perm:[1,0,3,2] row_mask:0xf bank_mask:0xf bound_ctrl:1
	v_pk_fma_f32 v[230:231], v[150:151], v[208:209], v[230:231]
	v_add_f32_dpp v226, v226, v226 quad_perm:[1,0,3,2] row_mask:0xf bank_mask:0xf bound_ctrl:1
	v_add_f32_dpp v238, v238, v238 quad_perm:[2,3,0,1] row_mask:0xf bank_mask:0xf bound_ctrl:1
	v_pk_fma_f32 v[232:233], v[152:153], v[210:211], v[232:233]
	v_add_f32_dpp v226, v226, v226 quad_perm:[2,3,0,1] row_mask:0xf bank_mask:0xf bound_ctrl:1
	v_add_f32_dpp v238, v238, v238 row_half_mirror row_mask:0xf bank_mask:0xf bound_ctrl:1
	v_pk_fma_f32 v[234:235], v[154:155], v[212:213], v[234:235]
	v_add_f32_dpp v226, v226, v226 row_half_mirror row_mask:0xf bank_mask:0xf bound_ctrl:1
	v_pk_fma_f32 v[148:149], v[190:191], v[226:227], v[228:229] op_sel_hi:[1,0,1]
	v_pk_fma_f32 v[150:151], v[192:193], v[226:227], v[230:231] op_sel_hi:[1,0,1]
	v_pk_mul_f32 v[236:237], v[148:149], v[214:215]
	v_pk_fma_f32 v[152:153], v[194:195], v[226:227], v[232:233] op_sel_hi:[1,0,1]
	v_pk_fma_f32 v[236:237], v[150:151], v[216:217], v[236:237]
	v_pk_fma_f32 v[154:155], v[196:197], v[226:227], v[234:235] op_sel_hi:[1,0,1]
	v_pk_fma_f32 v[236:237], v[152:153], v[218:219], v[236:237]
	v_cndmask_b32_e64 v168, v168, v238, s[14:15]
	v_pk_fma_f32 v[236:237], v[154:155], v[220:221], v[236:237]
	ds_read_b128 v[182:185], v239 offset:28416
	ds_read_b128 v[186:189], v239 offset:28432
	ds_read_b128 v[190:193], v239 offset:36608
	ds_read_b128 v[194:197], v239 offset:36624
	ds_read_b32 v222, v240 offset:42880
	ds_read_b128 v[198:201], v239 offset:20224
	ds_read_b128 v[202:205], v239 offset:20240
	ds_read_b128 v[206:209], v239 offset:12032
	ds_read_b128 v[210:213], v239 offset:12048
	ds_read_b128 v[214:217], v239 offset:3840
	ds_read_b128 v[218:221], v239 offset:3856
	s_waitcnt lgkmcnt(11)
	v_add_f32_e32 v169, v236, v237
	v_pk_mul_f32 v[224:225], v[148:149], v[44:45]
	v_pk_mul_f32 v[228:229], v[60:61], v[84:85] op_sel_hi:[1,0]
	v_pk_fma_f32 v[224:225], v[150:151], v[46:47], v[224:225]
	v_pk_mul_f32 v[230:231], v[62:63], v[84:85] op_sel_hi:[1,0]
	v_pk_fma_f32 v[224:225], v[152:153], v[48:49], v[224:225]
	v_pk_mul_f32 v[232:233], v[64:65], v[84:85] op_sel_hi:[1,0]
	v_pk_fma_f32 v[224:225], v[154:155], v[50:51], v[224:225]
	v_pk_mul_f32 v[234:235], v[66:67], v[84:85] op_sel_hi:[1,0]
	v_pk_fma_f32 v[228:229], v[148:149], v[68:69], v[228:229]
	v_add_f32_e32 v226, v224, v225
	v_add_f32_dpp v238, v169, v169 quad_perm:[1,0,3,2] row_mask:0xf bank_mask:0xf bound_ctrl:1
	v_pk_fma_f32 v[230:231], v[150:151], v[70:71], v[230:231]
	v_add_f32_dpp v226, v226, v226 quad_perm:[1,0,3,2] row_mask:0xf bank_mask:0xf bound_ctrl:1
	v_add_f32_dpp v238, v238, v238 quad_perm:[2,3,0,1] row_mask:0xf bank_mask:0xf bound_ctrl:1
	v_pk_fma_f32 v[232:233], v[152:153], v[72:73], v[232:233]
	v_add_f32_dpp v226, v226, v226 quad_perm:[2,3,0,1] row_mask:0xf bank_mask:0xf bound_ctrl:1
	v_add_f32_dpp v238, v238, v238 row_half_mirror row_mask:0xf bank_mask:0xf bound_ctrl:1
	v_pk_fma_f32 v[234:235], v[154:155], v[74:75], v[234:235]
	v_add_f32_dpp v226, v226, v226 row_half_mirror row_mask:0xf bank_mask:0xf bound_ctrl:1
	v_pk_fma_f32 v[148:149], v[52:53], v[226:227], v[228:229] op_sel_hi:[1,0,1]
	v_pk_fma_f32 v[150:151], v[54:55], v[226:227], v[230:231] op_sel_hi:[1,0,1]
	v_pk_mul_f32 v[236:237], v[148:149], v[76:77]
	v_pk_fma_f32 v[152:153], v[56:57], v[226:227], v[232:233] op_sel_hi:[1,0,1]
	v_pk_fma_f32 v[236:237], v[150:151], v[78:79], v[236:237]
	v_pk_fma_f32 v[154:155], v[58:59], v[226:227], v[234:235] op_sel_hi:[1,0,1]
	v_pk_fma_f32 v[236:237], v[152:153], v[80:81], v[236:237]
	v_cndmask_b32_e64 v168, v168, v238, s[16:17]
	v_pk_fma_f32 v[236:237], v[154:155], v[82:83], v[236:237]
	ds_read_b128 v[44:47], v239 offset:28672
	ds_read_b128 v[48:51], v239 offset:28688
	ds_read_b128 v[52:55], v239 offset:36864
	ds_read_b128 v[56:59], v239 offset:36880
	ds_read_b32 v84, v240 offset:43008
	ds_read_b128 v[60:63], v239 offset:20480
	ds_read_b128 v[64:67], v239 offset:20496
	ds_read_b128 v[68:71], v239 offset:12288
	ds_read_b128 v[72:75], v239 offset:12304
	ds_read_b128 v[76:79], v239 offset:4096
	ds_read_b128 v[80:83], v239 offset:4112
	s_waitcnt lgkmcnt(11)
	v_add_f32_e32 v169, v236, v237
	v_pk_mul_f32 v[224:225], v[148:149], v[182:183]
	v_pk_mul_f32 v[228:229], v[198:199], v[222:223] op_sel_hi:[1,0]
	v_pk_fma_f32 v[224:225], v[150:151], v[184:185], v[224:225]
	v_pk_mul_f32 v[230:231], v[200:201], v[222:223] op_sel_hi:[1,0]
	v_pk_fma_f32 v[224:225], v[152:153], v[186:187], v[224:225]
	v_pk_mul_f32 v[232:233], v[202:203], v[222:223] op_sel_hi:[1,0]
	v_pk_fma_f32 v[224:225], v[154:155], v[188:189], v[224:225]
	v_pk_mul_f32 v[234:235], v[204:205], v[222:223] op_sel_hi:[1,0]
	v_pk_fma_f32 v[228:229], v[148:149], v[206:207], v[228:229]
	v_add_f32_e32 v226, v224, v225
	v_add_f32_dpp v238, v169, v169 quad_perm:[1,0,3,2] row_mask:0xf bank_mask:0xf bound_ctrl:1
	v_pk_fma_f32 v[230:231], v[150:151], v[208:209], v[230:231]
	v_add_f32_dpp v226, v226, v226 quad_perm:[1,0,3,2] row_mask:0xf bank_mask:0xf bound_ctrl:1
	v_add_f32_dpp v238, v238, v238 quad_perm:[2,3,0,1] row_mask:0xf bank_mask:0xf bound_ctrl:1
	v_pk_fma_f32 v[232:233], v[152:153], v[210:211], v[232:233]
	v_add_f32_dpp v226, v226, v226 quad_perm:[2,3,0,1] row_mask:0xf bank_mask:0xf bound_ctrl:1
	v_add_f32_dpp v238, v238, v238 row_half_mirror row_mask:0xf bank_mask:0xf bound_ctrl:1
	v_pk_fma_f32 v[234:235], v[154:155], v[212:213], v[234:235]
	v_add_f32_dpp v226, v226, v226 row_half_mirror row_mask:0xf bank_mask:0xf bound_ctrl:1
	v_pk_fma_f32 v[148:149], v[190:191], v[226:227], v[228:229] op_sel_hi:[1,0,1]
	v_pk_fma_f32 v[150:151], v[192:193], v[226:227], v[230:231] op_sel_hi:[1,0,1]
	v_pk_mul_f32 v[236:237], v[148:149], v[214:215]
	v_pk_fma_f32 v[152:153], v[194:195], v[226:227], v[232:233] op_sel_hi:[1,0,1]
	v_pk_fma_f32 v[236:237], v[150:151], v[216:217], v[236:237]
	v_pk_fma_f32 v[154:155], v[196:197], v[226:227], v[234:235] op_sel_hi:[1,0,1]
	v_pk_fma_f32 v[236:237], v[152:153], v[218:219], v[236:237]
	v_cndmask_b32_e64 v168, v168, v238, s[18:19]
	v_pk_fma_f32 v[236:237], v[154:155], v[220:221], v[236:237]
	ds_read_b128 v[182:185], v239 offset:28928
	ds_read_b128 v[186:189], v239 offset:28944
	ds_read_b128 v[190:193], v239 offset:37120
	ds_read_b128 v[194:197], v239 offset:37136
	ds_read_b32 v222, v240 offset:43136
	ds_read_b128 v[198:201], v239 offset:20736
	ds_read_b128 v[202:205], v239 offset:20752
	ds_read_b128 v[206:209], v239 offset:12544
	ds_read_b128 v[210:213], v239 offset:12560
	ds_read_b128 v[214:217], v239 offset:4352
	ds_read_b128 v[218:221], v239 offset:4368
	s_waitcnt lgkmcnt(11)
	v_add_f32_e32 v169, v236, v237
	v_pk_mul_f32 v[224:225], v[148:149], v[44:45]
	v_pk_mul_f32 v[228:229], v[60:61], v[84:85] op_sel_hi:[1,0]
	v_pk_fma_f32 v[224:225], v[150:151], v[46:47], v[224:225]
	v_pk_mul_f32 v[230:231], v[62:63], v[84:85] op_sel_hi:[1,0]
	v_pk_fma_f32 v[224:225], v[152:153], v[48:49], v[224:225]
	v_pk_mul_f32 v[232:233], v[64:65], v[84:85] op_sel_hi:[1,0]
	v_pk_fma_f32 v[224:225], v[154:155], v[50:51], v[224:225]
	v_pk_mul_f32 v[234:235], v[66:67], v[84:85] op_sel_hi:[1,0]
	v_pk_fma_f32 v[228:229], v[148:149], v[68:69], v[228:229]
	v_add_f32_e32 v226, v224, v225
	v_add_f32_dpp v238, v169, v169 quad_perm:[1,0,3,2] row_mask:0xf bank_mask:0xf bound_ctrl:1
	v_pk_fma_f32 v[230:231], v[150:151], v[70:71], v[230:231]
	v_add_f32_dpp v226, v226, v226 quad_perm:[1,0,3,2] row_mask:0xf bank_mask:0xf bound_ctrl:1
	v_add_f32_dpp v238, v238, v238 quad_perm:[2,3,0,1] row_mask:0xf bank_mask:0xf bound_ctrl:1
	v_pk_fma_f32 v[232:233], v[152:153], v[72:73], v[232:233]
	v_add_f32_dpp v226, v226, v226 quad_perm:[2,3,0,1] row_mask:0xf bank_mask:0xf bound_ctrl:1
	v_add_f32_dpp v238, v238, v238 row_half_mirror row_mask:0xf bank_mask:0xf bound_ctrl:1
	v_pk_fma_f32 v[234:235], v[154:155], v[74:75], v[234:235]
	v_add_f32_dpp v226, v226, v226 row_half_mirror row_mask:0xf bank_mask:0xf bound_ctrl:1
	v_pk_fma_f32 v[148:149], v[52:53], v[226:227], v[228:229] op_sel_hi:[1,0,1]
	v_pk_fma_f32 v[150:151], v[54:55], v[226:227], v[230:231] op_sel_hi:[1,0,1]
	v_pk_mul_f32 v[236:237], v[148:149], v[76:77]
	v_pk_fma_f32 v[152:153], v[56:57], v[226:227], v[232:233] op_sel_hi:[1,0,1]
	v_pk_fma_f32 v[236:237], v[150:151], v[78:79], v[236:237]
	v_pk_fma_f32 v[154:155], v[58:59], v[226:227], v[234:235] op_sel_hi:[1,0,1]
	v_pk_fma_f32 v[236:237], v[152:153], v[80:81], v[236:237]
	v_cndmask_b32_e64 v168, v168, v238, s[4:5]
	v_pk_fma_f32 v[236:237], v[154:155], v[82:83], v[236:237]
	ds_write_b32 v241, v168 offset:2048
	ds_read_b128 v[44:47], v239 offset:29184
	ds_read_b128 v[48:51], v239 offset:29200
	ds_read_b128 v[52:55], v239 offset:37376
	ds_read_b128 v[56:59], v239 offset:37392
	ds_read_b32 v84, v240 offset:43264
	ds_read_b128 v[60:63], v239 offset:20992
	ds_read_b128 v[64:67], v239 offset:21008
	ds_read_b128 v[68:71], v239 offset:12800
	ds_read_b128 v[72:75], v239 offset:12816
	ds_read_b128 v[76:79], v239 offset:4608
	ds_read_b128 v[80:83], v239 offset:4624
	s_waitcnt lgkmcnt(11)
	v_add_f32_e32 v169, v236, v237
	v_pk_mul_f32 v[224:225], v[148:149], v[182:183]
	v_pk_mul_f32 v[228:229], v[198:199], v[222:223] op_sel_hi:[1,0]
	v_pk_fma_f32 v[224:225], v[150:151], v[184:185], v[224:225]
	v_pk_mul_f32 v[230:231], v[200:201], v[222:223] op_sel_hi:[1,0]
	v_pk_fma_f32 v[224:225], v[152:153], v[186:187], v[224:225]
	v_pk_mul_f32 v[232:233], v[202:203], v[222:223] op_sel_hi:[1,0]
	v_pk_fma_f32 v[224:225], v[154:155], v[188:189], v[224:225]
	v_pk_mul_f32 v[234:235], v[204:205], v[222:223] op_sel_hi:[1,0]
	v_pk_fma_f32 v[228:229], v[148:149], v[206:207], v[228:229]
	v_add_f32_e32 v226, v224, v225
	v_add_f32_dpp v238, v169, v169 quad_perm:[1,0,3,2] row_mask:0xf bank_mask:0xf bound_ctrl:1
	v_pk_fma_f32 v[230:231], v[150:151], v[208:209], v[230:231]
	v_add_f32_dpp v226, v226, v226 quad_perm:[1,0,3,2] row_mask:0xf bank_mask:0xf bound_ctrl:1
	v_add_f32_dpp v238, v238, v238 quad_perm:[2,3,0,1] row_mask:0xf bank_mask:0xf bound_ctrl:1
	v_pk_fma_f32 v[232:233], v[152:153], v[210:211], v[232:233]
	v_add_f32_dpp v226, v226, v226 quad_perm:[2,3,0,1] row_mask:0xf bank_mask:0xf bound_ctrl:1
	v_add_f32_dpp v238, v238, v238 row_half_mirror row_mask:0xf bank_mask:0xf bound_ctrl:1
	v_pk_fma_f32 v[234:235], v[154:155], v[212:213], v[234:235]
	v_add_f32_dpp v226, v226, v226 row_half_mirror row_mask:0xf bank_mask:0xf bound_ctrl:1
	v_pk_fma_f32 v[148:149], v[190:191], v[226:227], v[228:229] op_sel_hi:[1,0,1]
	v_pk_fma_f32 v[150:151], v[192:193], v[226:227], v[230:231] op_sel_hi:[1,0,1]
	v_pk_mul_f32 v[236:237], v[148:149], v[214:215]
	v_pk_fma_f32 v[152:153], v[194:195], v[226:227], v[232:233] op_sel_hi:[1,0,1]
	v_pk_fma_f32 v[236:237], v[150:151], v[216:217], v[236:237]
	v_pk_fma_f32 v[154:155], v[196:197], v[226:227], v[234:235] op_sel_hi:[1,0,1]
	v_pk_fma_f32 v[236:237], v[152:153], v[218:219], v[236:237]
	v_cndmask_b32_e64 v168, v168, v238, s[6:7]
	v_pk_fma_f32 v[236:237], v[154:155], v[220:221], v[236:237]
	ds_read_b128 v[182:185], v239 offset:29440
	ds_read_b128 v[186:189], v239 offset:29456
	ds_read_b128 v[190:193], v239 offset:37632
	ds_read_b128 v[194:197], v239 offset:37648
	ds_read_b32 v222, v240 offset:43392
	ds_read_b128 v[198:201], v239 offset:21248
	ds_read_b128 v[202:205], v239 offset:21264
	ds_read_b128 v[206:209], v239 offset:13056
	ds_read_b128 v[210:213], v239 offset:13072
	ds_read_b128 v[214:217], v239 offset:4864
	ds_read_b128 v[218:221], v239 offset:4880
	s_waitcnt lgkmcnt(11)
	v_add_f32_e32 v169, v236, v237
	v_pk_mul_f32 v[224:225], v[148:149], v[44:45]
	v_pk_mul_f32 v[228:229], v[60:61], v[84:85] op_sel_hi:[1,0]
	v_pk_fma_f32 v[224:225], v[150:151], v[46:47], v[224:225]
	v_pk_mul_f32 v[230:231], v[62:63], v[84:85] op_sel_hi:[1,0]
	v_pk_fma_f32 v[224:225], v[152:153], v[48:49], v[224:225]
	v_pk_mul_f32 v[232:233], v[64:65], v[84:85] op_sel_hi:[1,0]
	v_pk_fma_f32 v[224:225], v[154:155], v[50:51], v[224:225]
	v_pk_mul_f32 v[234:235], v[66:67], v[84:85] op_sel_hi:[1,0]
	v_pk_fma_f32 v[228:229], v[148:149], v[68:69], v[228:229]
	v_add_f32_e32 v226, v224, v225
	v_add_f32_dpp v238, v169, v169 quad_perm:[1,0,3,2] row_mask:0xf bank_mask:0xf bound_ctrl:1
	v_pk_fma_f32 v[230:231], v[150:151], v[70:71], v[230:231]
	v_add_f32_dpp v226, v226, v226 quad_perm:[1,0,3,2] row_mask:0xf bank_mask:0xf bound_ctrl:1
	v_add_f32_dpp v238, v238, v238 quad_perm:[2,3,0,1] row_mask:0xf bank_mask:0xf bound_ctrl:1
	v_pk_fma_f32 v[232:233], v[152:153], v[72:73], v[232:233]
	v_add_f32_dpp v226, v226, v226 quad_perm:[2,3,0,1] row_mask:0xf bank_mask:0xf bound_ctrl:1
	v_add_f32_dpp v238, v238, v238 row_half_mirror row_mask:0xf bank_mask:0xf bound_ctrl:1
	v_pk_fma_f32 v[234:235], v[154:155], v[74:75], v[234:235]
	v_add_f32_dpp v226, v226, v226 row_half_mirror row_mask:0xf bank_mask:0xf bound_ctrl:1
	v_pk_fma_f32 v[148:149], v[52:53], v[226:227], v[228:229] op_sel_hi:[1,0,1]
	v_pk_fma_f32 v[150:151], v[54:55], v[226:227], v[230:231] op_sel_hi:[1,0,1]
	v_pk_mul_f32 v[236:237], v[148:149], v[76:77]
	v_pk_fma_f32 v[152:153], v[56:57], v[226:227], v[232:233] op_sel_hi:[1,0,1]
	v_pk_fma_f32 v[236:237], v[150:151], v[78:79], v[236:237]
	v_pk_fma_f32 v[154:155], v[58:59], v[226:227], v[234:235] op_sel_hi:[1,0,1]
	v_pk_fma_f32 v[236:237], v[152:153], v[80:81], v[236:237]
	v_cndmask_b32_e64 v168, v168, v238, s[8:9]
	v_pk_fma_f32 v[236:237], v[154:155], v[82:83], v[236:237]
	ds_read_b128 v[44:47], v239 offset:29696
	ds_read_b128 v[48:51], v239 offset:29712
	ds_read_b128 v[52:55], v239 offset:37888
	ds_read_b128 v[56:59], v239 offset:37904
	ds_read_b32 v84, v240 offset:43520
	ds_read_b128 v[60:63], v239 offset:21504
	ds_read_b128 v[64:67], v239 offset:21520
	ds_read_b128 v[68:71], v239 offset:13312
	ds_read_b128 v[72:75], v239 offset:13328
	ds_read_b128 v[76:79], v239 offset:5120
	ds_read_b128 v[80:83], v239 offset:5136
	s_waitcnt lgkmcnt(11)
	v_add_f32_e32 v169, v236, v237
	v_pk_mul_f32 v[224:225], v[148:149], v[182:183]
	v_pk_mul_f32 v[228:229], v[198:199], v[222:223] op_sel_hi:[1,0]
	v_pk_fma_f32 v[224:225], v[150:151], v[184:185], v[224:225]
	v_pk_mul_f32 v[230:231], v[200:201], v[222:223] op_sel_hi:[1,0]
	v_pk_fma_f32 v[224:225], v[152:153], v[186:187], v[224:225]
	v_pk_mul_f32 v[232:233], v[202:203], v[222:223] op_sel_hi:[1,0]
	v_pk_fma_f32 v[224:225], v[154:155], v[188:189], v[224:225]
	v_pk_mul_f32 v[234:235], v[204:205], v[222:223] op_sel_hi:[1,0]
	v_pk_fma_f32 v[228:229], v[148:149], v[206:207], v[228:229]
	v_add_f32_e32 v226, v224, v225
	v_add_f32_dpp v238, v169, v169 quad_perm:[1,0,3,2] row_mask:0xf bank_mask:0xf bound_ctrl:1
	v_pk_fma_f32 v[230:231], v[150:151], v[208:209], v[230:231]
	v_add_f32_dpp v226, v226, v226 quad_perm:[1,0,3,2] row_mask:0xf bank_mask:0xf bound_ctrl:1
	v_add_f32_dpp v238, v238, v238 quad_perm:[2,3,0,1] row_mask:0xf bank_mask:0xf bound_ctrl:1
	v_pk_fma_f32 v[232:233], v[152:153], v[210:211], v[232:233]
	v_add_f32_dpp v226, v226, v226 quad_perm:[2,3,0,1] row_mask:0xf bank_mask:0xf bound_ctrl:1
	v_add_f32_dpp v238, v238, v238 row_half_mirror row_mask:0xf bank_mask:0xf bound_ctrl:1
	v_pk_fma_f32 v[234:235], v[154:155], v[212:213], v[234:235]
	v_add_f32_dpp v226, v226, v226 row_half_mirror row_mask:0xf bank_mask:0xf bound_ctrl:1
	v_pk_fma_f32 v[148:149], v[190:191], v[226:227], v[228:229] op_sel_hi:[1,0,1]
	v_pk_fma_f32 v[150:151], v[192:193], v[226:227], v[230:231] op_sel_hi:[1,0,1]
	v_pk_mul_f32 v[236:237], v[148:149], v[214:215]
	v_pk_fma_f32 v[152:153], v[194:195], v[226:227], v[232:233] op_sel_hi:[1,0,1]
	v_pk_fma_f32 v[236:237], v[150:151], v[216:217], v[236:237]
	v_pk_fma_f32 v[154:155], v[196:197], v[226:227], v[234:235] op_sel_hi:[1,0,1]
	v_pk_fma_f32 v[236:237], v[152:153], v[218:219], v[236:237]
	v_cndmask_b32_e64 v168, v168, v238, s[10:11]
	v_pk_fma_f32 v[236:237], v[154:155], v[220:221], v[236:237]
	ds_read_b128 v[182:185], v239 offset:29952
	ds_read_b128 v[186:189], v239 offset:29968
	ds_read_b128 v[190:193], v239 offset:38144
	ds_read_b128 v[194:197], v239 offset:38160
	ds_read_b32 v222, v240 offset:43648
	ds_read_b128 v[198:201], v239 offset:21760
	ds_read_b128 v[202:205], v239 offset:21776
	ds_read_b128 v[206:209], v239 offset:13568
	ds_read_b128 v[210:213], v239 offset:13584
	ds_read_b128 v[214:217], v239 offset:5376
	ds_read_b128 v[218:221], v239 offset:5392
	s_waitcnt lgkmcnt(11)
	v_add_f32_e32 v169, v236, v237
	v_pk_mul_f32 v[224:225], v[148:149], v[44:45]
	v_pk_mul_f32 v[228:229], v[60:61], v[84:85] op_sel_hi:[1,0]
	v_pk_fma_f32 v[224:225], v[150:151], v[46:47], v[224:225]
	v_pk_mul_f32 v[230:231], v[62:63], v[84:85] op_sel_hi:[1,0]
	v_pk_fma_f32 v[224:225], v[152:153], v[48:49], v[224:225]
	v_pk_mul_f32 v[232:233], v[64:65], v[84:85] op_sel_hi:[1,0]
	v_pk_fma_f32 v[224:225], v[154:155], v[50:51], v[224:225]
	v_pk_mul_f32 v[234:235], v[66:67], v[84:85] op_sel_hi:[1,0]
	v_pk_fma_f32 v[228:229], v[148:149], v[68:69], v[228:229]
	v_add_f32_e32 v226, v224, v225
	v_add_f32_dpp v238, v169, v169 quad_perm:[1,0,3,2] row_mask:0xf bank_mask:0xf bound_ctrl:1
	v_pk_fma_f32 v[230:231], v[150:151], v[70:71], v[230:231]
	v_add_f32_dpp v226, v226, v226 quad_perm:[1,0,3,2] row_mask:0xf bank_mask:0xf bound_ctrl:1
	v_add_f32_dpp v238, v238, v238 quad_perm:[2,3,0,1] row_mask:0xf bank_mask:0xf bound_ctrl:1
	v_pk_fma_f32 v[232:233], v[152:153], v[72:73], v[232:233]
	v_add_f32_dpp v226, v226, v226 quad_perm:[2,3,0,1] row_mask:0xf bank_mask:0xf bound_ctrl:1
	v_add_f32_dpp v238, v238, v238 row_half_mirror row_mask:0xf bank_mask:0xf bound_ctrl:1
	v_pk_fma_f32 v[234:235], v[154:155], v[74:75], v[234:235]
	v_add_f32_dpp v226, v226, v226 row_half_mirror row_mask:0xf bank_mask:0xf bound_ctrl:1
	v_pk_fma_f32 v[148:149], v[52:53], v[226:227], v[228:229] op_sel_hi:[1,0,1]
	v_pk_fma_f32 v[150:151], v[54:55], v[226:227], v[230:231] op_sel_hi:[1,0,1]
	v_pk_mul_f32 v[236:237], v[148:149], v[76:77]
	v_pk_fma_f32 v[152:153], v[56:57], v[226:227], v[232:233] op_sel_hi:[1,0,1]
	v_pk_fma_f32 v[236:237], v[150:151], v[78:79], v[236:237]
	v_pk_fma_f32 v[154:155], v[58:59], v[226:227], v[234:235] op_sel_hi:[1,0,1]
	v_pk_fma_f32 v[236:237], v[152:153], v[80:81], v[236:237]
	v_cndmask_b32_e64 v168, v168, v238, s[12:13]
	v_pk_fma_f32 v[236:237], v[154:155], v[82:83], v[236:237]
	ds_read_b128 v[44:47], v239 offset:30208
	ds_read_b128 v[48:51], v239 offset:30224
	ds_read_b128 v[52:55], v239 offset:38400
	ds_read_b128 v[56:59], v239 offset:38416
	ds_read_b32 v84, v240 offset:43776
	ds_read_b128 v[60:63], v239 offset:22016
	ds_read_b128 v[64:67], v239 offset:22032
	ds_read_b128 v[68:71], v239 offset:13824
	ds_read_b128 v[72:75], v239 offset:13840
	ds_read_b128 v[76:79], v239 offset:5632
	ds_read_b128 v[80:83], v239 offset:5648
	s_waitcnt lgkmcnt(11)
	v_add_f32_e32 v169, v236, v237
	v_pk_mul_f32 v[224:225], v[148:149], v[182:183]
	v_pk_mul_f32 v[228:229], v[198:199], v[222:223] op_sel_hi:[1,0]
	v_pk_fma_f32 v[224:225], v[150:151], v[184:185], v[224:225]
	v_pk_mul_f32 v[230:231], v[200:201], v[222:223] op_sel_hi:[1,0]
	v_pk_fma_f32 v[224:225], v[152:153], v[186:187], v[224:225]
	v_pk_mul_f32 v[232:233], v[202:203], v[222:223] op_sel_hi:[1,0]
	v_pk_fma_f32 v[224:225], v[154:155], v[188:189], v[224:225]
	v_pk_mul_f32 v[234:235], v[204:205], v[222:223] op_sel_hi:[1,0]
	v_pk_fma_f32 v[228:229], v[148:149], v[206:207], v[228:229]
	v_add_f32_e32 v226, v224, v225
	v_add_f32_dpp v238, v169, v169 quad_perm:[1,0,3,2] row_mask:0xf bank_mask:0xf bound_ctrl:1
	v_pk_fma_f32 v[230:231], v[150:151], v[208:209], v[230:231]
	v_add_f32_dpp v226, v226, v226 quad_perm:[1,0,3,2] row_mask:0xf bank_mask:0xf bound_ctrl:1
	v_add_f32_dpp v238, v238, v238 quad_perm:[2,3,0,1] row_mask:0xf bank_mask:0xf bound_ctrl:1
	v_pk_fma_f32 v[232:233], v[152:153], v[210:211], v[232:233]
	v_add_f32_dpp v226, v226, v226 quad_perm:[2,3,0,1] row_mask:0xf bank_mask:0xf bound_ctrl:1
	v_add_f32_dpp v238, v238, v238 row_half_mirror row_mask:0xf bank_mask:0xf bound_ctrl:1
	v_pk_fma_f32 v[234:235], v[154:155], v[212:213], v[234:235]
	v_add_f32_dpp v226, v226, v226 row_half_mirror row_mask:0xf bank_mask:0xf bound_ctrl:1
	v_pk_fma_f32 v[148:149], v[190:191], v[226:227], v[228:229] op_sel_hi:[1,0,1]
	v_pk_fma_f32 v[150:151], v[192:193], v[226:227], v[230:231] op_sel_hi:[1,0,1]
	v_pk_mul_f32 v[236:237], v[148:149], v[214:215]
	v_pk_fma_f32 v[152:153], v[194:195], v[226:227], v[232:233] op_sel_hi:[1,0,1]
	v_pk_fma_f32 v[236:237], v[150:151], v[216:217], v[236:237]
	v_pk_fma_f32 v[154:155], v[196:197], v[226:227], v[234:235] op_sel_hi:[1,0,1]
	v_pk_fma_f32 v[236:237], v[152:153], v[218:219], v[236:237]
	v_cndmask_b32_e64 v168, v168, v238, s[14:15]
	v_pk_fma_f32 v[236:237], v[154:155], v[220:221], v[236:237]
	ds_read_b128 v[182:185], v239 offset:30464
	ds_read_b128 v[186:189], v239 offset:30480
	ds_read_b128 v[190:193], v239 offset:38656
	ds_read_b128 v[194:197], v239 offset:38672
	ds_read_b32 v222, v240 offset:43904
	ds_read_b128 v[198:201], v239 offset:22272
	ds_read_b128 v[202:205], v239 offset:22288
	ds_read_b128 v[206:209], v239 offset:14080
	ds_read_b128 v[210:213], v239 offset:14096
	ds_read_b128 v[214:217], v239 offset:5888
	ds_read_b128 v[218:221], v239 offset:5904
	s_waitcnt lgkmcnt(11)
	v_add_f32_e32 v169, v236, v237
	v_pk_mul_f32 v[224:225], v[148:149], v[44:45]
	v_pk_mul_f32 v[228:229], v[60:61], v[84:85] op_sel_hi:[1,0]
	v_pk_fma_f32 v[224:225], v[150:151], v[46:47], v[224:225]
	v_pk_mul_f32 v[230:231], v[62:63], v[84:85] op_sel_hi:[1,0]
	v_pk_fma_f32 v[224:225], v[152:153], v[48:49], v[224:225]
	v_pk_mul_f32 v[232:233], v[64:65], v[84:85] op_sel_hi:[1,0]
	v_pk_fma_f32 v[224:225], v[154:155], v[50:51], v[224:225]
	v_pk_mul_f32 v[234:235], v[66:67], v[84:85] op_sel_hi:[1,0]
	v_pk_fma_f32 v[228:229], v[148:149], v[68:69], v[228:229]
	v_add_f32_e32 v226, v224, v225
	v_add_f32_dpp v238, v169, v169 quad_perm:[1,0,3,2] row_mask:0xf bank_mask:0xf bound_ctrl:1
	v_pk_fma_f32 v[230:231], v[150:151], v[70:71], v[230:231]
	v_add_f32_dpp v226, v226, v226 quad_perm:[1,0,3,2] row_mask:0xf bank_mask:0xf bound_ctrl:1
	v_add_f32_dpp v238, v238, v238 quad_perm:[2,3,0,1] row_mask:0xf bank_mask:0xf bound_ctrl:1
	v_pk_fma_f32 v[232:233], v[152:153], v[72:73], v[232:233]
	v_add_f32_dpp v226, v226, v226 quad_perm:[2,3,0,1] row_mask:0xf bank_mask:0xf bound_ctrl:1
	v_add_f32_dpp v238, v238, v238 row_half_mirror row_mask:0xf bank_mask:0xf bound_ctrl:1
	v_pk_fma_f32 v[234:235], v[154:155], v[74:75], v[234:235]
	v_add_f32_dpp v226, v226, v226 row_half_mirror row_mask:0xf bank_mask:0xf bound_ctrl:1
	v_pk_fma_f32 v[148:149], v[52:53], v[226:227], v[228:229] op_sel_hi:[1,0,1]
	v_pk_fma_f32 v[150:151], v[54:55], v[226:227], v[230:231] op_sel_hi:[1,0,1]
	v_pk_mul_f32 v[236:237], v[148:149], v[76:77]
	v_pk_fma_f32 v[152:153], v[56:57], v[226:227], v[232:233] op_sel_hi:[1,0,1]
	v_pk_fma_f32 v[236:237], v[150:151], v[78:79], v[236:237]
	v_pk_fma_f32 v[154:155], v[58:59], v[226:227], v[234:235] op_sel_hi:[1,0,1]
	v_pk_fma_f32 v[236:237], v[152:153], v[80:81], v[236:237]
	v_cndmask_b32_e64 v168, v168, v238, s[16:17]
	v_pk_fma_f32 v[236:237], v[154:155], v[82:83], v[236:237]
	ds_read_b128 v[44:47], v239 offset:30720
	ds_read_b128 v[48:51], v239 offset:30736
	ds_read_b128 v[52:55], v239 offset:38912
	ds_read_b128 v[56:59], v239 offset:38928
	ds_read_b32 v84, v240 offset:44032
	ds_read_b128 v[60:63], v239 offset:22528
	ds_read_b128 v[64:67], v239 offset:22544
	ds_read_b128 v[68:71], v239 offset:14336
	ds_read_b128 v[72:75], v239 offset:14352
	ds_read_b128 v[76:79], v239 offset:6144
	ds_read_b128 v[80:83], v239 offset:6160
	s_waitcnt lgkmcnt(11)
	v_add_f32_e32 v169, v236, v237
	v_pk_mul_f32 v[224:225], v[148:149], v[182:183]
	v_pk_mul_f32 v[228:229], v[198:199], v[222:223] op_sel_hi:[1,0]
	v_pk_fma_f32 v[224:225], v[150:151], v[184:185], v[224:225]
	v_pk_mul_f32 v[230:231], v[200:201], v[222:223] op_sel_hi:[1,0]
	v_pk_fma_f32 v[224:225], v[152:153], v[186:187], v[224:225]
	v_pk_mul_f32 v[232:233], v[202:203], v[222:223] op_sel_hi:[1,0]
	v_pk_fma_f32 v[224:225], v[154:155], v[188:189], v[224:225]
	v_pk_mul_f32 v[234:235], v[204:205], v[222:223] op_sel_hi:[1,0]
	v_pk_fma_f32 v[228:229], v[148:149], v[206:207], v[228:229]
	v_add_f32_e32 v226, v224, v225
	v_add_f32_dpp v238, v169, v169 quad_perm:[1,0,3,2] row_mask:0xf bank_mask:0xf bound_ctrl:1
	v_pk_fma_f32 v[230:231], v[150:151], v[208:209], v[230:231]
	v_add_f32_dpp v226, v226, v226 quad_perm:[1,0,3,2] row_mask:0xf bank_mask:0xf bound_ctrl:1
	v_add_f32_dpp v238, v238, v238 quad_perm:[2,3,0,1] row_mask:0xf bank_mask:0xf bound_ctrl:1
	v_pk_fma_f32 v[232:233], v[152:153], v[210:211], v[232:233]
	v_add_f32_dpp v226, v226, v226 quad_perm:[2,3,0,1] row_mask:0xf bank_mask:0xf bound_ctrl:1
	v_add_f32_dpp v238, v238, v238 row_half_mirror row_mask:0xf bank_mask:0xf bound_ctrl:1
	v_pk_fma_f32 v[234:235], v[154:155], v[212:213], v[234:235]
	v_add_f32_dpp v226, v226, v226 row_half_mirror row_mask:0xf bank_mask:0xf bound_ctrl:1
	v_pk_fma_f32 v[148:149], v[190:191], v[226:227], v[228:229] op_sel_hi:[1,0,1]
	v_pk_fma_f32 v[150:151], v[192:193], v[226:227], v[230:231] op_sel_hi:[1,0,1]
	v_pk_mul_f32 v[236:237], v[148:149], v[214:215]
	v_pk_fma_f32 v[152:153], v[194:195], v[226:227], v[232:233] op_sel_hi:[1,0,1]
	v_pk_fma_f32 v[236:237], v[150:151], v[216:217], v[236:237]
	v_pk_fma_f32 v[154:155], v[196:197], v[226:227], v[234:235] op_sel_hi:[1,0,1]
	v_pk_fma_f32 v[236:237], v[152:153], v[218:219], v[236:237]
	v_cndmask_b32_e64 v168, v168, v238, s[18:19]
	v_pk_fma_f32 v[236:237], v[154:155], v[220:221], v[236:237]
	ds_read_b128 v[182:185], v239 offset:30976
	ds_read_b128 v[186:189], v239 offset:30992
	ds_read_b128 v[190:193], v239 offset:39168
	ds_read_b128 v[194:197], v239 offset:39184
	ds_read_b32 v222, v240 offset:44160
	ds_read_b128 v[198:201], v239 offset:22784
	ds_read_b128 v[202:205], v239 offset:22800
	ds_read_b128 v[206:209], v239 offset:14592
	ds_read_b128 v[210:213], v239 offset:14608
	ds_read_b128 v[214:217], v239 offset:6400
	ds_read_b128 v[218:221], v239 offset:6416
	s_waitcnt lgkmcnt(11)
	v_add_f32_e32 v169, v236, v237
	v_pk_mul_f32 v[224:225], v[148:149], v[44:45]
	v_pk_mul_f32 v[228:229], v[60:61], v[84:85] op_sel_hi:[1,0]
	v_pk_fma_f32 v[224:225], v[150:151], v[46:47], v[224:225]
	v_pk_mul_f32 v[230:231], v[62:63], v[84:85] op_sel_hi:[1,0]
	v_pk_fma_f32 v[224:225], v[152:153], v[48:49], v[224:225]
	v_pk_mul_f32 v[232:233], v[64:65], v[84:85] op_sel_hi:[1,0]
	v_pk_fma_f32 v[224:225], v[154:155], v[50:51], v[224:225]
	v_pk_mul_f32 v[234:235], v[66:67], v[84:85] op_sel_hi:[1,0]
	v_pk_fma_f32 v[228:229], v[148:149], v[68:69], v[228:229]
	v_add_f32_e32 v226, v224, v225
	v_add_f32_dpp v238, v169, v169 quad_perm:[1,0,3,2] row_mask:0xf bank_mask:0xf bound_ctrl:1
	v_pk_fma_f32 v[230:231], v[150:151], v[70:71], v[230:231]
	v_add_f32_dpp v226, v226, v226 quad_perm:[1,0,3,2] row_mask:0xf bank_mask:0xf bound_ctrl:1
	v_add_f32_dpp v238, v238, v238 quad_perm:[2,3,0,1] row_mask:0xf bank_mask:0xf bound_ctrl:1
	v_pk_fma_f32 v[232:233], v[152:153], v[72:73], v[232:233]
	v_add_f32_dpp v226, v226, v226 quad_perm:[2,3,0,1] row_mask:0xf bank_mask:0xf bound_ctrl:1
	v_add_f32_dpp v238, v238, v238 row_half_mirror row_mask:0xf bank_mask:0xf bound_ctrl:1
	v_pk_fma_f32 v[234:235], v[154:155], v[74:75], v[234:235]
	v_add_f32_dpp v226, v226, v226 row_half_mirror row_mask:0xf bank_mask:0xf bound_ctrl:1
	v_pk_fma_f32 v[148:149], v[52:53], v[226:227], v[228:229] op_sel_hi:[1,0,1]
	v_pk_fma_f32 v[150:151], v[54:55], v[226:227], v[230:231] op_sel_hi:[1,0,1]
	v_pk_mul_f32 v[236:237], v[148:149], v[76:77]
	v_pk_fma_f32 v[152:153], v[56:57], v[226:227], v[232:233] op_sel_hi:[1,0,1]
	v_pk_fma_f32 v[236:237], v[150:151], v[78:79], v[236:237]
	v_pk_fma_f32 v[154:155], v[58:59], v[226:227], v[234:235] op_sel_hi:[1,0,1]
	v_pk_fma_f32 v[236:237], v[152:153], v[80:81], v[236:237]
	v_cndmask_b32_e64 v168, v168, v238, s[4:5]
	v_pk_fma_f32 v[236:237], v[154:155], v[82:83], v[236:237]
	ds_write_b32 v241, v168 offset:3072
	ds_read_b128 v[44:47], v239 offset:31232
	ds_read_b128 v[48:51], v239 offset:31248
	ds_read_b128 v[52:55], v239 offset:39424
	ds_read_b128 v[56:59], v239 offset:39440
	ds_read_b32 v84, v240 offset:44288
	ds_read_b128 v[60:63], v239 offset:23040
	ds_read_b128 v[64:67], v239 offset:23056
	ds_read_b128 v[68:71], v239 offset:14848
	ds_read_b128 v[72:75], v239 offset:14864
	ds_read_b128 v[76:79], v239 offset:6656
	ds_read_b128 v[80:83], v239 offset:6672
	s_waitcnt lgkmcnt(11)
	v_add_f32_e32 v169, v236, v237
	v_pk_mul_f32 v[224:225], v[148:149], v[182:183]
	v_pk_mul_f32 v[228:229], v[198:199], v[222:223] op_sel_hi:[1,0]
	v_pk_fma_f32 v[224:225], v[150:151], v[184:185], v[224:225]
	v_pk_mul_f32 v[230:231], v[200:201], v[222:223] op_sel_hi:[1,0]
	v_pk_fma_f32 v[224:225], v[152:153], v[186:187], v[224:225]
	v_pk_mul_f32 v[232:233], v[202:203], v[222:223] op_sel_hi:[1,0]
	v_pk_fma_f32 v[224:225], v[154:155], v[188:189], v[224:225]
	v_pk_mul_f32 v[234:235], v[204:205], v[222:223] op_sel_hi:[1,0]
	v_pk_fma_f32 v[228:229], v[148:149], v[206:207], v[228:229]
	v_add_f32_e32 v226, v224, v225
	v_add_f32_dpp v238, v169, v169 quad_perm:[1,0,3,2] row_mask:0xf bank_mask:0xf bound_ctrl:1
	v_pk_fma_f32 v[230:231], v[150:151], v[208:209], v[230:231]
	v_add_f32_dpp v226, v226, v226 quad_perm:[1,0,3,2] row_mask:0xf bank_mask:0xf bound_ctrl:1
	v_add_f32_dpp v238, v238, v238 quad_perm:[2,3,0,1] row_mask:0xf bank_mask:0xf bound_ctrl:1
	v_pk_fma_f32 v[232:233], v[152:153], v[210:211], v[232:233]
	v_add_f32_dpp v226, v226, v226 quad_perm:[2,3,0,1] row_mask:0xf bank_mask:0xf bound_ctrl:1
	v_add_f32_dpp v238, v238, v238 row_half_mirror row_mask:0xf bank_mask:0xf bound_ctrl:1
	v_pk_fma_f32 v[234:235], v[154:155], v[212:213], v[234:235]
	v_add_f32_dpp v226, v226, v226 row_half_mirror row_mask:0xf bank_mask:0xf bound_ctrl:1
	v_pk_fma_f32 v[148:149], v[190:191], v[226:227], v[228:229] op_sel_hi:[1,0,1]
	v_pk_fma_f32 v[150:151], v[192:193], v[226:227], v[230:231] op_sel_hi:[1,0,1]
	v_pk_mul_f32 v[236:237], v[148:149], v[214:215]
	v_pk_fma_f32 v[152:153], v[194:195], v[226:227], v[232:233] op_sel_hi:[1,0,1]
	v_pk_fma_f32 v[236:237], v[150:151], v[216:217], v[236:237]
	v_pk_fma_f32 v[154:155], v[196:197], v[226:227], v[234:235] op_sel_hi:[1,0,1]
	v_pk_fma_f32 v[236:237], v[152:153], v[218:219], v[236:237]
	v_cndmask_b32_e64 v168, v168, v238, s[6:7]
	v_pk_fma_f32 v[236:237], v[154:155], v[220:221], v[236:237]
	ds_read_b128 v[182:185], v239 offset:31488
	ds_read_b128 v[186:189], v239 offset:31504
	ds_read_b128 v[190:193], v239 offset:39680
	ds_read_b128 v[194:197], v239 offset:39696
	ds_read_b32 v222, v240 offset:44416
	ds_read_b128 v[198:201], v239 offset:23296
	ds_read_b128 v[202:205], v239 offset:23312
	ds_read_b128 v[206:209], v239 offset:15104
	ds_read_b128 v[210:213], v239 offset:15120
	ds_read_b128 v[214:217], v239 offset:6912
	ds_read_b128 v[218:221], v239 offset:6928
	s_waitcnt lgkmcnt(11)
	v_add_f32_e32 v169, v236, v237
	v_pk_mul_f32 v[224:225], v[148:149], v[44:45]
	v_pk_mul_f32 v[228:229], v[60:61], v[84:85] op_sel_hi:[1,0]
	v_pk_fma_f32 v[224:225], v[150:151], v[46:47], v[224:225]
	v_pk_mul_f32 v[230:231], v[62:63], v[84:85] op_sel_hi:[1,0]
	v_pk_fma_f32 v[224:225], v[152:153], v[48:49], v[224:225]
	v_pk_mul_f32 v[232:233], v[64:65], v[84:85] op_sel_hi:[1,0]
	v_pk_fma_f32 v[224:225], v[154:155], v[50:51], v[224:225]
	v_pk_mul_f32 v[234:235], v[66:67], v[84:85] op_sel_hi:[1,0]
	v_pk_fma_f32 v[228:229], v[148:149], v[68:69], v[228:229]
	v_add_f32_e32 v226, v224, v225
	v_add_f32_dpp v238, v169, v169 quad_perm:[1,0,3,2] row_mask:0xf bank_mask:0xf bound_ctrl:1
	v_pk_fma_f32 v[230:231], v[150:151], v[70:71], v[230:231]
	v_add_f32_dpp v226, v226, v226 quad_perm:[1,0,3,2] row_mask:0xf bank_mask:0xf bound_ctrl:1
	v_add_f32_dpp v238, v238, v238 quad_perm:[2,3,0,1] row_mask:0xf bank_mask:0xf bound_ctrl:1
	v_pk_fma_f32 v[232:233], v[152:153], v[72:73], v[232:233]
	v_add_f32_dpp v226, v226, v226 quad_perm:[2,3,0,1] row_mask:0xf bank_mask:0xf bound_ctrl:1
	v_add_f32_dpp v238, v238, v238 row_half_mirror row_mask:0xf bank_mask:0xf bound_ctrl:1
	v_pk_fma_f32 v[234:235], v[154:155], v[74:75], v[234:235]
	v_add_f32_dpp v226, v226, v226 row_half_mirror row_mask:0xf bank_mask:0xf bound_ctrl:1
	v_pk_fma_f32 v[148:149], v[52:53], v[226:227], v[228:229] op_sel_hi:[1,0,1]
	v_pk_fma_f32 v[150:151], v[54:55], v[226:227], v[230:231] op_sel_hi:[1,0,1]
	v_pk_mul_f32 v[236:237], v[148:149], v[76:77]
	v_pk_fma_f32 v[152:153], v[56:57], v[226:227], v[232:233] op_sel_hi:[1,0,1]
	v_pk_fma_f32 v[236:237], v[150:151], v[78:79], v[236:237]
	v_pk_fma_f32 v[154:155], v[58:59], v[226:227], v[234:235] op_sel_hi:[1,0,1]
	v_pk_fma_f32 v[236:237], v[152:153], v[80:81], v[236:237]
	v_cndmask_b32_e64 v168, v168, v238, s[8:9]
	v_pk_fma_f32 v[236:237], v[154:155], v[82:83], v[236:237]
	ds_read_b128 v[44:47], v239 offset:31744
	ds_read_b128 v[48:51], v239 offset:31760
	ds_read_b128 v[52:55], v239 offset:39936
	ds_read_b128 v[56:59], v239 offset:39952
	ds_read_b32 v84, v240 offset:44544
	ds_read_b128 v[60:63], v239 offset:23552
	ds_read_b128 v[64:67], v239 offset:23568
	ds_read_b128 v[68:71], v239 offset:15360
	ds_read_b128 v[72:75], v239 offset:15376
	ds_read_b128 v[76:79], v239 offset:7168
	ds_read_b128 v[80:83], v239 offset:7184
	s_waitcnt lgkmcnt(11)
	v_add_f32_e32 v169, v236, v237
	v_pk_mul_f32 v[224:225], v[148:149], v[182:183]
	v_pk_mul_f32 v[228:229], v[198:199], v[222:223] op_sel_hi:[1,0]
	v_pk_fma_f32 v[224:225], v[150:151], v[184:185], v[224:225]
	v_pk_mul_f32 v[230:231], v[200:201], v[222:223] op_sel_hi:[1,0]
	v_pk_fma_f32 v[224:225], v[152:153], v[186:187], v[224:225]
	v_pk_mul_f32 v[232:233], v[202:203], v[222:223] op_sel_hi:[1,0]
	v_pk_fma_f32 v[224:225], v[154:155], v[188:189], v[224:225]
	v_pk_mul_f32 v[234:235], v[204:205], v[222:223] op_sel_hi:[1,0]
	v_pk_fma_f32 v[228:229], v[148:149], v[206:207], v[228:229]
	v_add_f32_e32 v226, v224, v225
	v_add_f32_dpp v238, v169, v169 quad_perm:[1,0,3,2] row_mask:0xf bank_mask:0xf bound_ctrl:1
	v_pk_fma_f32 v[230:231], v[150:151], v[208:209], v[230:231]
	v_add_f32_dpp v226, v226, v226 quad_perm:[1,0,3,2] row_mask:0xf bank_mask:0xf bound_ctrl:1
	v_add_f32_dpp v238, v238, v238 quad_perm:[2,3,0,1] row_mask:0xf bank_mask:0xf bound_ctrl:1
	v_pk_fma_f32 v[232:233], v[152:153], v[210:211], v[232:233]
	v_add_f32_dpp v226, v226, v226 quad_perm:[2,3,0,1] row_mask:0xf bank_mask:0xf bound_ctrl:1
	v_add_f32_dpp v238, v238, v238 row_half_mirror row_mask:0xf bank_mask:0xf bound_ctrl:1
	v_pk_fma_f32 v[234:235], v[154:155], v[212:213], v[234:235]
	v_add_f32_dpp v226, v226, v226 row_half_mirror row_mask:0xf bank_mask:0xf bound_ctrl:1
	v_pk_fma_f32 v[148:149], v[190:191], v[226:227], v[228:229] op_sel_hi:[1,0,1]
	v_pk_fma_f32 v[150:151], v[192:193], v[226:227], v[230:231] op_sel_hi:[1,0,1]
	v_pk_mul_f32 v[236:237], v[148:149], v[214:215]
	v_pk_fma_f32 v[152:153], v[194:195], v[226:227], v[232:233] op_sel_hi:[1,0,1]
	v_pk_fma_f32 v[236:237], v[150:151], v[216:217], v[236:237]
	v_pk_fma_f32 v[154:155], v[196:197], v[226:227], v[234:235] op_sel_hi:[1,0,1]
	v_pk_fma_f32 v[236:237], v[152:153], v[218:219], v[236:237]
	v_cndmask_b32_e64 v168, v168, v238, s[10:11]
	v_pk_fma_f32 v[236:237], v[154:155], v[220:221], v[236:237]
	ds_read_b128 v[182:185], v239 offset:32000
	ds_read_b128 v[186:189], v239 offset:32016
	ds_read_b128 v[190:193], v239 offset:40192
	ds_read_b128 v[194:197], v239 offset:40208
	ds_read_b32 v222, v240 offset:44672
	ds_read_b128 v[198:201], v239 offset:23808
	ds_read_b128 v[202:205], v239 offset:23824
	ds_read_b128 v[206:209], v239 offset:15616
	ds_read_b128 v[210:213], v239 offset:15632
	ds_read_b128 v[214:217], v239 offset:7424
	ds_read_b128 v[218:221], v239 offset:7440
	s_waitcnt lgkmcnt(11)
	v_add_f32_e32 v169, v236, v237
	v_pk_mul_f32 v[224:225], v[148:149], v[44:45]
	v_pk_mul_f32 v[228:229], v[60:61], v[84:85] op_sel_hi:[1,0]
	v_pk_fma_f32 v[224:225], v[150:151], v[46:47], v[224:225]
	v_pk_mul_f32 v[230:231], v[62:63], v[84:85] op_sel_hi:[1,0]
	v_pk_fma_f32 v[224:225], v[152:153], v[48:49], v[224:225]
	v_pk_mul_f32 v[232:233], v[64:65], v[84:85] op_sel_hi:[1,0]
	v_pk_fma_f32 v[224:225], v[154:155], v[50:51], v[224:225]
	v_pk_mul_f32 v[234:235], v[66:67], v[84:85] op_sel_hi:[1,0]
	v_pk_fma_f32 v[228:229], v[148:149], v[68:69], v[228:229]
	v_add_f32_e32 v226, v224, v225
	v_add_f32_dpp v238, v169, v169 quad_perm:[1,0,3,2] row_mask:0xf bank_mask:0xf bound_ctrl:1
	v_pk_fma_f32 v[230:231], v[150:151], v[70:71], v[230:231]
	v_add_f32_dpp v226, v226, v226 quad_perm:[1,0,3,2] row_mask:0xf bank_mask:0xf bound_ctrl:1
	v_add_f32_dpp v238, v238, v238 quad_perm:[2,3,0,1] row_mask:0xf bank_mask:0xf bound_ctrl:1
	v_pk_fma_f32 v[232:233], v[152:153], v[72:73], v[232:233]
	v_add_f32_dpp v226, v226, v226 quad_perm:[2,3,0,1] row_mask:0xf bank_mask:0xf bound_ctrl:1
	v_add_f32_dpp v238, v238, v238 row_half_mirror row_mask:0xf bank_mask:0xf bound_ctrl:1
	v_pk_fma_f32 v[234:235], v[154:155], v[74:75], v[234:235]
	v_add_f32_dpp v226, v226, v226 row_half_mirror row_mask:0xf bank_mask:0xf bound_ctrl:1
	v_pk_fma_f32 v[148:149], v[52:53], v[226:227], v[228:229] op_sel_hi:[1,0,1]
	v_pk_fma_f32 v[150:151], v[54:55], v[226:227], v[230:231] op_sel_hi:[1,0,1]
	v_pk_mul_f32 v[236:237], v[148:149], v[76:77]
	v_pk_fma_f32 v[152:153], v[56:57], v[226:227], v[232:233] op_sel_hi:[1,0,1]
	v_pk_fma_f32 v[236:237], v[150:151], v[78:79], v[236:237]
	v_pk_fma_f32 v[154:155], v[58:59], v[226:227], v[234:235] op_sel_hi:[1,0,1]
	v_pk_fma_f32 v[236:237], v[152:153], v[80:81], v[236:237]
	v_cndmask_b32_e64 v168, v168, v238, s[12:13]
	v_pk_fma_f32 v[236:237], v[154:155], v[82:83], v[236:237]
	ds_read_b128 v[44:47], v239 offset:32256
	ds_read_b128 v[48:51], v239 offset:32272
	ds_read_b128 v[52:55], v239 offset:40448
	ds_read_b128 v[56:59], v239 offset:40464
	ds_read_b32 v84, v240 offset:44800
	ds_read_b128 v[60:63], v239 offset:24064
	ds_read_b128 v[64:67], v239 offset:24080
	ds_read_b128 v[68:71], v239 offset:15872
	ds_read_b128 v[72:75], v239 offset:15888
	ds_read_b128 v[76:79], v239 offset:7680
	ds_read_b128 v[80:83], v239 offset:7696
	s_waitcnt lgkmcnt(11)
	v_add_f32_e32 v169, v236, v237
	v_pk_mul_f32 v[224:225], v[148:149], v[182:183]
	v_pk_mul_f32 v[228:229], v[198:199], v[222:223] op_sel_hi:[1,0]
	v_pk_fma_f32 v[224:225], v[150:151], v[184:185], v[224:225]
	v_pk_mul_f32 v[230:231], v[200:201], v[222:223] op_sel_hi:[1,0]
	v_pk_fma_f32 v[224:225], v[152:153], v[186:187], v[224:225]
	v_pk_mul_f32 v[232:233], v[202:203], v[222:223] op_sel_hi:[1,0]
	v_pk_fma_f32 v[224:225], v[154:155], v[188:189], v[224:225]
	v_pk_mul_f32 v[234:235], v[204:205], v[222:223] op_sel_hi:[1,0]
	v_pk_fma_f32 v[228:229], v[148:149], v[206:207], v[228:229]
	v_add_f32_e32 v226, v224, v225
	v_add_f32_dpp v238, v169, v169 quad_perm:[1,0,3,2] row_mask:0xf bank_mask:0xf bound_ctrl:1
	v_pk_fma_f32 v[230:231], v[150:151], v[208:209], v[230:231]
	v_add_f32_dpp v226, v226, v226 quad_perm:[1,0,3,2] row_mask:0xf bank_mask:0xf bound_ctrl:1
	v_add_f32_dpp v238, v238, v238 quad_perm:[2,3,0,1] row_mask:0xf bank_mask:0xf bound_ctrl:1
	v_pk_fma_f32 v[232:233], v[152:153], v[210:211], v[232:233]
	v_add_f32_dpp v226, v226, v226 quad_perm:[2,3,0,1] row_mask:0xf bank_mask:0xf bound_ctrl:1
	v_add_f32_dpp v238, v238, v238 row_half_mirror row_mask:0xf bank_mask:0xf bound_ctrl:1
	v_pk_fma_f32 v[234:235], v[154:155], v[212:213], v[234:235]
	v_add_f32_dpp v226, v226, v226 row_half_mirror row_mask:0xf bank_mask:0xf bound_ctrl:1
	v_pk_fma_f32 v[148:149], v[190:191], v[226:227], v[228:229] op_sel_hi:[1,0,1]
	v_pk_fma_f32 v[150:151], v[192:193], v[226:227], v[230:231] op_sel_hi:[1,0,1]
	v_pk_mul_f32 v[236:237], v[148:149], v[214:215]
	v_pk_fma_f32 v[152:153], v[194:195], v[226:227], v[232:233] op_sel_hi:[1,0,1]
	v_pk_fma_f32 v[236:237], v[150:151], v[216:217], v[236:237]
	v_pk_fma_f32 v[154:155], v[196:197], v[226:227], v[234:235] op_sel_hi:[1,0,1]
	v_pk_fma_f32 v[236:237], v[152:153], v[218:219], v[236:237]
	v_cndmask_b32_e64 v168, v168, v238, s[14:15]
	v_pk_fma_f32 v[236:237], v[154:155], v[220:221], v[236:237]
	ds_read_b128 v[182:185], v239 offset:32512
	ds_read_b128 v[186:189], v239 offset:32528
	ds_read_b128 v[190:193], v239 offset:40704
	ds_read_b128 v[194:197], v239 offset:40720
	ds_read_b32 v222, v240 offset:44928
	ds_read_b128 v[198:201], v239 offset:24320
	ds_read_b128 v[202:205], v239 offset:24336
	ds_read_b128 v[206:209], v239 offset:16128
	ds_read_b128 v[210:213], v239 offset:16144
	ds_read_b128 v[214:217], v239 offset:7936
	ds_read_b128 v[218:221], v239 offset:7952
	s_waitcnt lgkmcnt(11)
	v_add_f32_e32 v169, v236, v237
	v_pk_mul_f32 v[224:225], v[148:149], v[44:45]
	v_pk_mul_f32 v[228:229], v[60:61], v[84:85] op_sel_hi:[1,0]
	v_pk_fma_f32 v[224:225], v[150:151], v[46:47], v[224:225]
	v_pk_mul_f32 v[230:231], v[62:63], v[84:85] op_sel_hi:[1,0]
	v_pk_fma_f32 v[224:225], v[152:153], v[48:49], v[224:225]
	v_pk_mul_f32 v[232:233], v[64:65], v[84:85] op_sel_hi:[1,0]
	v_pk_fma_f32 v[224:225], v[154:155], v[50:51], v[224:225]
	v_pk_mul_f32 v[234:235], v[66:67], v[84:85] op_sel_hi:[1,0]
	v_pk_fma_f32 v[228:229], v[148:149], v[68:69], v[228:229]
	v_add_f32_e32 v226, v224, v225
	v_add_f32_dpp v238, v169, v169 quad_perm:[1,0,3,2] row_mask:0xf bank_mask:0xf bound_ctrl:1
	v_pk_fma_f32 v[230:231], v[150:151], v[70:71], v[230:231]
	v_add_f32_dpp v226, v226, v226 quad_perm:[1,0,3,2] row_mask:0xf bank_mask:0xf bound_ctrl:1
	v_add_f32_dpp v238, v238, v238 quad_perm:[2,3,0,1] row_mask:0xf bank_mask:0xf bound_ctrl:1
	v_pk_fma_f32 v[232:233], v[152:153], v[72:73], v[232:233]
	v_add_f32_dpp v226, v226, v226 quad_perm:[2,3,0,1] row_mask:0xf bank_mask:0xf bound_ctrl:1
	v_add_f32_dpp v238, v238, v238 row_half_mirror row_mask:0xf bank_mask:0xf bound_ctrl:1
	v_pk_fma_f32 v[234:235], v[154:155], v[74:75], v[234:235]
	v_add_f32_dpp v226, v226, v226 row_half_mirror row_mask:0xf bank_mask:0xf bound_ctrl:1
	v_pk_fma_f32 v[148:149], v[52:53], v[226:227], v[228:229] op_sel_hi:[1,0,1]
	v_pk_fma_f32 v[150:151], v[54:55], v[226:227], v[230:231] op_sel_hi:[1,0,1]
	v_pk_mul_f32 v[236:237], v[148:149], v[76:77]
	v_pk_fma_f32 v[152:153], v[56:57], v[226:227], v[232:233] op_sel_hi:[1,0,1]
	v_pk_fma_f32 v[236:237], v[150:151], v[78:79], v[236:237]
	v_pk_fma_f32 v[154:155], v[58:59], v[226:227], v[234:235] op_sel_hi:[1,0,1]
	v_pk_fma_f32 v[236:237], v[152:153], v[80:81], v[236:237]
	v_cndmask_b32_e64 v168, v168, v238, s[16:17]
	v_pk_fma_f32 v[236:237], v[154:155], v[82:83], v[236:237]
	s_waitcnt lgkmcnt(0)
	v_add_f32_e32 v169, v236, v237
	v_pk_mul_f32 v[224:225], v[148:149], v[182:183]
	v_pk_mul_f32 v[228:229], v[198:199], v[222:223] op_sel_hi:[1,0]
	v_pk_fma_f32 v[224:225], v[150:151], v[184:185], v[224:225]
	v_pk_mul_f32 v[230:231], v[200:201], v[222:223] op_sel_hi:[1,0]
	v_pk_fma_f32 v[224:225], v[152:153], v[186:187], v[224:225]
	v_pk_mul_f32 v[232:233], v[202:203], v[222:223] op_sel_hi:[1,0]
	v_pk_fma_f32 v[224:225], v[154:155], v[188:189], v[224:225]
	v_pk_mul_f32 v[234:235], v[204:205], v[222:223] op_sel_hi:[1,0]
	v_pk_fma_f32 v[228:229], v[148:149], v[206:207], v[228:229]
	v_add_f32_e32 v226, v224, v225
	v_add_f32_dpp v238, v169, v169 quad_perm:[1,0,3,2] row_mask:0xf bank_mask:0xf bound_ctrl:1
	v_pk_fma_f32 v[230:231], v[150:151], v[208:209], v[230:231]
	v_add_f32_dpp v226, v226, v226 quad_perm:[1,0,3,2] row_mask:0xf bank_mask:0xf bound_ctrl:1
	v_add_f32_dpp v238, v238, v238 quad_perm:[2,3,0,1] row_mask:0xf bank_mask:0xf bound_ctrl:1
	v_pk_fma_f32 v[232:233], v[152:153], v[210:211], v[232:233]
	v_add_f32_dpp v226, v226, v226 quad_perm:[2,3,0,1] row_mask:0xf bank_mask:0xf bound_ctrl:1
	v_add_f32_dpp v238, v238, v238 row_half_mirror row_mask:0xf bank_mask:0xf bound_ctrl:1
	v_pk_fma_f32 v[234:235], v[154:155], v[212:213], v[234:235]
	v_add_f32_dpp v226, v226, v226 row_half_mirror row_mask:0xf bank_mask:0xf bound_ctrl:1
	v_pk_fma_f32 v[148:149], v[190:191], v[226:227], v[228:229] op_sel_hi:[1,0,1]
	v_pk_fma_f32 v[150:151], v[192:193], v[226:227], v[230:231] op_sel_hi:[1,0,1]
	v_pk_mul_f32 v[236:237], v[148:149], v[214:215]
	v_pk_fma_f32 v[152:153], v[194:195], v[226:227], v[232:233] op_sel_hi:[1,0,1]
	v_pk_fma_f32 v[236:237], v[150:151], v[216:217], v[236:237]
	v_pk_fma_f32 v[154:155], v[196:197], v[226:227], v[234:235] op_sel_hi:[1,0,1]
	v_pk_fma_f32 v[236:237], v[152:153], v[218:219], v[236:237]
	v_cndmask_b32_e64 v168, v168, v238, s[18:19]
	v_pk_fma_f32 v[236:237], v[154:155], v[220:221], v[236:237]
	s_nop 0
	v_add_f32_e32 v169, v236, v237
	s_branch .LBB0_476

.LBB0_760:
	s_or_b64 exec, exec, s[4:5]
	s_mov_b64 s[4:5], exec
	v_mbcnt_lo_u32_b32 v0, s4, 0
	v_mbcnt_hi_u32_b32 v0, s5, v0
	v_cmp_eq_u32_e32 vcc, 0, v0
	s_waitcnt vmcnt(0)
	s_and_saveexec_b64 s[6:7], vcc
	s_cbranch_execz .LBB0_762
	s_bcnt1_i32_b64 s4, s[4:5]
	v_mov_b32_e32 v0, s4
	global_atomic_add v148, v0, s[2:3] offset:1024

.LBB0_1456:
	s_or_b64 exec, exec, s[6:7]
	s_mov_b64 s[6:7], exec
	v_mbcnt_lo_u32_b32 v0, s6, 0
	v_mbcnt_hi_u32_b32 v0, s7, v0
	v_cmp_eq_u32_e32 vcc, 0, v0
	s_waitcnt vmcnt(0)
	s_and_saveexec_b64 s[8:9], vcc
	s_cbranch_execz .LBB0_1458
	s_bcnt1_i32_b64 s6, s[6:7]
	v_mov_b32_e32 v0, 0x2000
	v_mov_b32_e32 v1, s6
	global_atomic_add v0, v1, s[4:5] offset:1024
.LBB0_1458:
	s_or_b64 exec, exec, s[8:9]
	buffer_inv sc1
	s_waitcnt vmcnt(0)

.LBB0_1558:
	s_or_b64 exec, exec, s[10:11]
	s_mov_b64 s[10:11], exec
	v_mbcnt_lo_u32_b32 v48, s10, 0
	v_mbcnt_hi_u32_b32 v48, s11, v48
	v_cmp_eq_u32_e32 vcc, 0, v48
	s_waitcnt vmcnt(0)
	s_and_saveexec_b64 s[20:21], vcc
	s_cbranch_execz .LBB0_1560
	s_bcnt1_i32_b64 s10, s[10:11]
	v_mov_b32_e32 v48, 0x2000
	v_mov_b32_e32 v49, s10
	global_atomic_add v48, v49, s[8:9] offset:1024
.LBB0_1560:
	s_or_b64 exec, exec, s[20:21]
	buffer_inv sc1
	s_waitcnt vmcnt(0)
